# EpiGU + rope table prefetch (one block/row ahead, counted waits)
# speedup vs baseline: 1.0429x; 1.0062x over previous
; #define PG8_STAGE(bufoff, gbase, voff) do { _Pragma("unroll") for (int _i = 0; _i < 2; ++_i) \
;         __builtin_amdgcn_global_load_lds((const unsigned*)((const char*)(gbase) + (voff)[_i]), (LAS unsigned*)(lds + (bufoff) + ldsw + _i * 8192), 16, 0, 0); } while (0)
; #define PG8_LDA(dst, b, h) do { _Pragma("unroll") for (int m = 0; m < 4; ++m) _Pragma("unroll") for (int k = 0; k < 2; ++k) dst[m][k] = *(const LAS bf16x8*)(lds + PG8_SA(b, h) + aoff + m * 2048 + k * 1024); } while (0)
; #define PG8_LDB(dst, b, h) do { _Pragma("unroll") for (int n = 0; n < 2; ++n) _Pragma("unroll") for (int k = 0; k < 2; ++k) dst[n][k] = *(const LAS bf16x8*)(lds + PG8_SB(b, h) + boff + n * 2048 + k * 1024); } while (0)
; #define PG8_MMA(ai, bj, At, Bt) do { __builtin_amdgcn_s_setprio(1); _Pragma("unroll") for (int m = 0; m < 4; ++m) _Pragma("unroll") for (int n = 0; n < 2; ++n) _Pragma("unroll") for (int k = 0; k < 2; ++k) \
;         acc[ai][bj][m][n] = __builtin_amdgcn_mfma_f32_16x16x32_bf16(Bt[n][k], At[m][k], acc[ai][bj][m][n], 0, 0, 0); __builtin_amdgcn_s_setprio(0); } while (0)
; #define PG8_WAIT_L(n) asm volatile("s_waitcnt lgkmcnt(" #n ")" ::: "memory")
; #define PG8_BAR __builtin_amdgcn_s_barrier()
; #define PG8_SCHED __builtin_amdgcn_sched_barrier(0)
; template <class Epi, class Sched>
; __device__ __forceinline__ void gemm_phase(LAS unsigned char* lds, const Gemm g, const Sched& S, const Epi& E) {
;     ...
;             const char* a1 = cA + (size_t)(t + 1) * kstep;
;             const char* a2 = last ? nA : cA + (size_t)(t + 2) * kstep; const char* b2 = last ? nB : cB + (size_t)(t + 2) * kstep;
;             const char* a3 = a2 + kstep; const char* b3 = b2 + kstep;
;             PG8_LDB(B0, 0, 0); PG8_SCHED; PG8_LDA(At, 0, 0); PG8_STAGE(PG8_SA(1, 1), a1 + hstep, voffA);
;             PG8_WAIT_L(8); PG8_BAR; PG8_WAIT_L(0); PG8_MMA(0, 0, At, B0); PG8_BAR; PG8_SCHED;
;             PG8_LDB(B1, 0, 1); PG8_STAGE(PG8_SB(0, 0), b2, voffB);
;             PG8_BAR; PG8_WAIT_L(0); PG8_MMA(0, 1, At, B1); PG8_BAR;
;             PG8_LDA(At, 0, 1); PG8_STAGE(PG8_SA(0, 0), a2, voffA);
;             PG8_BAR; PG8_WAIT_L(0); PG8_MMA(1, 0, At, B0); PG8_BAR; PG8_SCHED;
.LBB0_77:
	s_add_u32 s10, s8, 0xfffc0080
	s_addc_u32 s11, s9, -1
	s_add_i32 s51, 0, 0x10000
	v_add_u32_e32 v140, s51, v196
	ds_read_b128 v[128:131], v140
	ds_read_b128 v[132:135], v140 offset:1024
	ds_read_b128 v[136:139], v140 offset:2048
	ds_read_b128 v[140:143], v140 offset:3072
	s_cmp_eq_u32 s50, 12
	s_cselect_b32 s49, s7, s11
	s_cselect_b32 s48, s13, s10
	s_cselect_b32 s11, s33, s67
	s_cselect_b32 s10, s41, s43
	v_lshl_add_u64 v[152:153], s[8:9], 0, v[176:177]
	s_add_i32 m0, s56, 0xc000
	ds_read_b128 v[144:147], v197
	ds_read_b128 v[178:181], v197 offset:1024
	ds_read_b128 v[182:185], v197 offset:2048
	ds_read_b128 v[186:189], v197 offset:3072
	ds_read_b128 v[190:193], v197 offset:4096
	ds_read_b128 v[198:201], v197 offset:5120
	ds_read_b128 v[202:205], v197 offset:6144
	ds_read_b128 v[206:209], v197 offset:7168
	global_load_lds_dwordx4 v[152:153], off
	v_lshl_add_u64 v[152:153], s[8:9], 0, v[150:151]
	s_add_i32 m0, s56, 0xe000
	s_nop 0
	global_load_lds_dwordx4 v[152:153], off
	s_waitcnt lgkmcnt(8)
	s_barrier
	s_waitcnt lgkmcnt(0)
	s_setprio 1
	s_waitcnt lgkmcnt(0)
	v_mfma_f32_16x16x32_bf16 v[124:127], v[128:131], v[144:147], v[124:127]
	v_mfma_f32_16x16x32_bf16 v[92:95], v[136:139], v[144:147], v[92:95]
	v_mfma_f32_16x16x32_bf16 v[112:115], v[128:131], v[182:185], v[112:115]
	v_mfma_f32_16x16x32_bf16 v[80:83], v[136:139], v[182:185], v[80:83]
	v_mfma_f32_16x16x32_bf16 v[108:111], v[128:131], v[190:193], v[108:111]
	v_mfma_f32_16x16x32_bf16 v[76:79], v[136:139], v[190:193], v[76:79]
	v_mfma_f32_16x16x32_bf16 v[120:123], v[128:131], v[202:205], v[120:123]
	v_mfma_f32_16x16x32_bf16 v[88:91], v[136:139], v[202:205], v[88:91]
	v_mfma_f32_16x16x32_bf16 v[124:127], v[132:135], v[178:181], v[124:127]
	v_mfma_f32_16x16x32_bf16 v[92:95], v[140:143], v[178:181], v[92:95]
	v_mfma_f32_16x16x32_bf16 v[112:115], v[132:135], v[186:189], v[112:115]
	v_mfma_f32_16x16x32_bf16 v[80:83], v[140:143], v[186:189], v[80:83]
	v_mfma_f32_16x16x32_bf16 v[108:111], v[132:135], v[198:201], v[108:111]
	v_mfma_f32_16x16x32_bf16 v[76:79], v[140:143], v[198:201], v[76:79]
	v_mfma_f32_16x16x32_bf16 v[120:123], v[132:135], v[206:209], v[120:123]
	v_mfma_f32_16x16x32_bf16 v[88:91], v[140:143], v[206:209], v[88:91]
	s_setprio 0
	s_barrier
	s_add_i32 s70, 0, 0x14000
	v_add_u32_e32 v152, s70, v196
	s_add_i32 s51, s51, s55
	ds_read_b128 v[210:213], v152
	ds_read_b128 v[214:217], v152 offset:1024
	ds_read_b128 v[218:221], v152 offset:2048
	ds_read_b128 v[238:241], v152 offset:3072
	v_lshl_add_u64 v[152:153], s[10:11], 0, v[154:155]
	s_mov_b32 m0, s51
	v_lshl_add_u64 v[156:157], s[10:11], 0, v[148:149]
	global_load_lds_dwordx4 v[152:153], off
	s_add_i32 m0, s51, 0x2000
	s_nop 0
	global_load_lds_dwordx4 v[156:157], off
	s_barrier
	s_waitcnt lgkmcnt(0)
	s_setprio 1
	s_waitcnt lgkmcnt(0)
	v_mfma_f32_16x16x32_bf16 v[116:119], v[210:213], v[144:147], v[116:119]
	v_mfma_f32_16x16x32_bf16 v[84:87], v[218:221], v[144:147], v[84:87]
	v_mfma_f32_16x16x32_bf16 v[104:107], v[210:213], v[182:185], v[104:107]
	v_mfma_f32_16x16x32_bf16 v[72:75], v[218:221], v[182:185], v[72:75]
	v_mfma_f32_16x16x32_bf16 v[100:103], v[210:213], v[190:193], v[100:103]
	v_mfma_f32_16x16x32_bf16 v[68:71], v[218:221], v[190:193], v[68:71]
	v_mfma_f32_16x16x32_bf16 v[96:99], v[210:213], v[202:205], v[96:99]
	v_mfma_f32_16x16x32_bf16 v[64:67], v[218:221], v[202:205], v[64:67]
	v_mfma_f32_16x16x32_bf16 v[116:119], v[214:217], v[178:181], v[116:119]
	v_mfma_f32_16x16x32_bf16 v[84:87], v[238:241], v[178:181], v[84:87]
	v_mfma_f32_16x16x32_bf16 v[104:107], v[214:217], v[186:189], v[104:107]
	v_mfma_f32_16x16x32_bf16 v[72:75], v[238:241], v[186:189], v[72:75]
	v_mfma_f32_16x16x32_bf16 v[100:103], v[214:217], v[198:201], v[100:103]
	v_mfma_f32_16x16x32_bf16 v[68:71], v[238:241], v[198:201], v[68:71]
	v_mfma_f32_16x16x32_bf16 v[96:99], v[214:217], v[206:209], v[96:99]
	v_mfma_f32_16x16x32_bf16 v[64:67], v[238:241], v[206:209], v[64:67]
	s_setprio 0
	s_mov_b32 m0, s56
	v_lshl_add_u64 v[222:223], s[48:49], 0, v[154:155]
	s_barrier
	ds_read_b128 v[144:147], v197 offset:16384
	ds_read_b128 v[178:181], v197 offset:17408
	ds_read_b128 v[182:185], v197 offset:18432
	ds_read_b128 v[186:189], v197 offset:19456
	ds_read_b128 v[190:193], v197 offset:20480
	ds_read_b128 v[198:201], v197 offset:21504
	ds_read_b128 v[202:205], v197 offset:22528
	ds_read_b128 v[206:209], v197 offset:23552
	global_load_lds_dwordx4 v[222:223], off
	v_lshl_add_u64 v[232:233], s[48:49], 0, v[148:149]
	s_mov_b32 m0, s57
	s_nop 0
	global_load_lds_dwordx4 v[232:233], off
	s_barrier
	s_waitcnt lgkmcnt(0)
	s_setprio 1
	s_waitcnt lgkmcnt(0)
	v_mfma_f32_16x16x32_bf16 v[60:63], v[128:131], v[144:147], v[60:63]
	v_mfma_f32_16x16x32_bf16 v[28:31], v[136:139], v[144:147], v[28:31]
	v_mfma_f32_16x16x32_bf16 v[48:51], v[128:131], v[182:185], v[48:51]
	v_mfma_f32_16x16x32_bf16 v[16:19], v[136:139], v[182:185], v[16:19]
	v_mfma_f32_16x16x32_bf16 v[44:47], v[128:131], v[190:193], v[44:47]
	v_mfma_f32_16x16x32_bf16 v[12:15], v[136:139], v[190:193], v[12:15]
	v_mfma_f32_16x16x32_bf16 v[56:59], v[128:131], v[202:205], v[56:59]
	v_mfma_f32_16x16x32_bf16 v[24:27], v[136:139], v[202:205], v[24:27]
	v_mfma_f32_16x16x32_bf16 v[60:63], v[132:135], v[178:181], v[60:63]
	v_mfma_f32_16x16x32_bf16 v[28:31], v[140:143], v[178:181], v[28:31]
	v_mfma_f32_16x16x32_bf16 v[48:51], v[132:135], v[186:189], v[48:51]
	v_mfma_f32_16x16x32_bf16 v[16:19], v[140:143], v[186:189], v[16:19]
	v_mfma_f32_16x16x32_bf16 v[44:47], v[132:135], v[198:201], v[44:47]
	v_mfma_f32_16x16x32_bf16 v[12:15], v[140:143], v[198:201], v[12:15]
	v_mfma_f32_16x16x32_bf16 v[56:59], v[132:135], v[206:209], v[56:59]
	v_mfma_f32_16x16x32_bf16 v[24:27], v[140:143], v[206:209], v[24:27]
	s_setprio 0
	s_barrier
; #define PG8_STAGE(bufoff, gbase, voff) do { _Pragma("unroll") for (int _i = 0; _i < 2; ++_i) \
;         __builtin_amdgcn_global_load_lds((const unsigned*)((const char*)(gbase) + (voff)[_i]), (LAS unsigned*)(lds + (bufoff) + ldsw + _i * 8192), 16, 0, 0); } while (0)
; #define PG8_LDA(dst, b, h) do { _Pragma("unroll") for (int m = 0; m < 4; ++m) _Pragma("unroll") for (int k = 0; k < 2; ++k) dst[m][k] = *(const LAS bf16x8*)(lds + PG8_SA(b, h) + aoff + m * 2048 + k * 1024); } while (0)
; #define PG8_LDB(dst, b, h) do { _Pragma("unroll") for (int n = 0; n < 2; ++n) _Pragma("unroll") for (int k = 0; k < 2; ++k) dst[n][k] = *(const LAS bf16x8*)(lds + PG8_SB(b, h) + boff + n * 2048 + k * 1024); } while (0)
; #define PG8_MMA(ai, bj, At, Bt) do { __builtin_amdgcn_s_setprio(1); _Pragma("unroll") for (int m = 0; m < 4; ++m) _Pragma("unroll") for (int n = 0; n < 2; ++n) _Pragma("unroll") for (int k = 0; k < 2; ++k) \
;         acc[ai][bj][m][n] = __builtin_amdgcn_mfma_f32_16x16x32_bf16(Bt[n][k], At[m][k], acc[ai][bj][m][n], 0, 0, 0); __builtin_amdgcn_s_setprio(0); } while (0)
; #define PG8_WAIT_V(n) asm volatile("s_waitcnt vmcnt(" #n ")" ::: "memory")
; #define PG8_WAIT_L(n) asm volatile("s_waitcnt lgkmcnt(" #n ")" ::: "memory")
; #define PG8_BAR __builtin_amdgcn_s_barrier()
; #define PG8_SCHED __builtin_amdgcn_sched_barrier(0)
; template <class Epi, class Sched>
; __device__ __forceinline__ void gemm_phase(LAS unsigned char* lds, const Gemm g, const Sched& S, const Epi& E) {
;     ...
;             PG8_STAGE(PG8_SB(0, 1), b2 + hstep, voffB);
;             PG8_WAIT_V(6); PG8_BAR; PG8_MMA(1, 1, At, B1); PG8_BAR;
;             PG8_LDB(B0, 1, 0); PG8_SCHED; PG8_LDA(At, 1, 0); PG8_STAGE(PG8_SA(0, 1), a2 + hstep, voffA);
;             PG8_WAIT_L(8); PG8_BAR; PG8_WAIT_L(0); PG8_MMA(0, 0, At, B0); PG8_BAR; PG8_SCHED;
;             PG8_LDB(B1, 1, 1); PG8_STAGE(PG8_SB(1, 0), b3, voffB);
;             PG8_BAR; PG8_WAIT_L(0); PG8_MMA(0, 1, At, B1); PG8_BAR;
;             PG8_LDA(At, 1, 1); PG8_STAGE(PG8_SA(1, 0), a3, voffA);
	s_add_u32 s68, s10, 0x40000
	s_addc_u32 s69, s11, 0
	s_add_i32 s51, s70, s55
	v_lshl_add_u64 v[128:129], s[68:69], 0, v[154:155]
	s_mov_b32 m0, s51
	s_nop 0
	global_load_lds_dwordx4 v[128:129], off
	v_lshl_add_u64 v[128:129], s[68:69], 0, v[148:149]
	s_add_i32 m0, s51, 0x2000
	s_nop 0
	global_load_lds_dwordx4 v[128:129], off
	s_waitcnt vmcnt(6)
	s_barrier
	s_setprio 1
	v_mfma_f32_16x16x32_bf16 v[52:55], v[210:213], v[144:147], v[52:55]
	v_mfma_f32_16x16x32_bf16 v[20:23], v[218:221], v[144:147], v[20:23]
	v_mfma_f32_16x16x32_bf16 v[40:43], v[210:213], v[182:185], v[40:43]
	v_mfma_f32_16x16x32_bf16 v[8:11], v[218:221], v[182:185], v[8:11]
	v_mfma_f32_16x16x32_bf16 v[36:39], v[210:213], v[190:193], v[36:39]
	v_mfma_f32_16x16x32_bf16 v[4:7], v[218:221], v[190:193], v[4:7]
	v_mfma_f32_16x16x32_bf16 v[32:35], v[210:213], v[202:205], v[32:35]
	v_mfma_f32_16x16x32_bf16 v[0:3], v[218:221], v[202:205], v[0:3]
	v_mfma_f32_16x16x32_bf16 v[52:55], v[214:217], v[178:181], v[52:55]
	v_mfma_f32_16x16x32_bf16 v[20:23], v[238:241], v[178:181], v[20:23]
	v_mfma_f32_16x16x32_bf16 v[40:43], v[214:217], v[186:189], v[40:43]
	v_mfma_f32_16x16x32_bf16 v[8:11], v[238:241], v[186:189], v[8:11]
	v_mfma_f32_16x16x32_bf16 v[36:39], v[214:217], v[198:201], v[36:39]
	v_mfma_f32_16x16x32_bf16 v[4:7], v[238:241], v[198:201], v[4:7]
	v_mfma_f32_16x16x32_bf16 v[32:35], v[214:217], v[206:209], v[32:35]
	v_mfma_f32_16x16x32_bf16 v[0:3], v[238:241], v[206:209], v[0:3]
	s_setprio 0
	s_add_i32 s51, 0, 0x18000
	v_add_u32_e32 v140, s51, v196
	s_barrier
	ds_read_b128 v[128:131], v140
	ds_read_b128 v[132:135], v140 offset:1024
	ds_read_b128 v[136:139], v140 offset:2048
	ds_read_b128 v[140:143], v140 offset:3072
	s_add_u32 s48, s48, 0x40000
	s_addc_u32 s49, s49, 0
	s_mov_b32 m0, s58
	v_lshl_add_u64 v[210:211], s[48:49], 0, v[154:155]
	ds_read_b128 v[144:147], v197 offset:32768
	ds_read_b128 v[178:181], v197 offset:33792
	ds_read_b128 v[182:185], v197 offset:34816
	ds_read_b128 v[186:189], v197 offset:35840
	ds_read_b128 v[190:193], v197 offset:36864
	ds_read_b128 v[198:201], v197 offset:37888
	ds_read_b128 v[202:205], v197 offset:38912
	ds_read_b128 v[206:209], v197 offset:39936
	global_load_lds_dwordx4 v[210:211], off
	v_lshl_add_u64 v[210:211], s[48:49], 0, v[148:149]
	s_mov_b32 m0, s59
	s_nop 0
	global_load_lds_dwordx4 v[210:211], off
	s_waitcnt lgkmcnt(8)
	s_barrier
	s_waitcnt lgkmcnt(0)
	s_setprio 1
	s_waitcnt lgkmcnt(0)
	v_mfma_f32_16x16x32_bf16 v[124:127], v[128:131], v[144:147], v[124:127]
	v_mfma_f32_16x16x32_bf16 v[92:95], v[136:139], v[144:147], v[92:95]
	v_mfma_f32_16x16x32_bf16 v[112:115], v[128:131], v[182:185], v[112:115]
	v_mfma_f32_16x16x32_bf16 v[80:83], v[136:139], v[182:185], v[80:83]
	v_mfma_f32_16x16x32_bf16 v[108:111], v[128:131], v[190:193], v[108:111]
	v_mfma_f32_16x16x32_bf16 v[76:79], v[136:139], v[190:193], v[76:79]
	v_mfma_f32_16x16x32_bf16 v[120:123], v[128:131], v[202:205], v[120:123]
	v_mfma_f32_16x16x32_bf16 v[88:91], v[136:139], v[202:205], v[88:91]
	v_mfma_f32_16x16x32_bf16 v[124:127], v[132:135], v[178:181], v[124:127]
	v_mfma_f32_16x16x32_bf16 v[92:95], v[140:143], v[178:181], v[92:95]
	v_mfma_f32_16x16x32_bf16 v[112:115], v[132:135], v[186:189], v[112:115]
	v_mfma_f32_16x16x32_bf16 v[80:83], v[140:143], v[186:189], v[80:83]
	v_mfma_f32_16x16x32_bf16 v[108:111], v[132:135], v[198:201], v[108:111]
	v_mfma_f32_16x16x32_bf16 v[76:79], v[140:143], v[198:201], v[76:79]
	v_mfma_f32_16x16x32_bf16 v[120:123], v[132:135], v[206:209], v[120:123]
	v_mfma_f32_16x16x32_bf16 v[88:91], v[140:143], v[206:209], v[88:91]
	s_setprio 0
	s_barrier
	s_add_i32 s48, 0, 0x1c000
	s_add_i32 s49, s51, s55
	v_add_u32_e32 v224, s48, v196
	v_lshl_add_u64 v[152:153], v[152:153], 0, s[78:79]
	s_mov_b32 m0, s49
	ds_read_b128 v[210:213], v224
	ds_read_b128 v[214:217], v224 offset:1024
	ds_read_b128 v[218:221], v224 offset:2048
	ds_read_b128 v[238:241], v224 offset:3072
	global_load_lds_dwordx4 v[152:153], off
	v_lshl_add_u64 v[152:153], v[156:157], 0, s[78:79]
	s_add_i32 m0, s49, 0x2000
	s_nop 0
	global_load_lds_dwordx4 v[152:153], off
	s_barrier
	s_waitcnt lgkmcnt(0)
	s_setprio 1
	s_waitcnt lgkmcnt(0)
	v_mfma_f32_16x16x32_bf16 v[116:119], v[210:213], v[144:147], v[116:119]
	v_mfma_f32_16x16x32_bf16 v[84:87], v[218:221], v[144:147], v[84:87]
	v_mfma_f32_16x16x32_bf16 v[104:107], v[210:213], v[182:185], v[104:107]
	v_mfma_f32_16x16x32_bf16 v[72:75], v[218:221], v[182:185], v[72:75]
	v_mfma_f32_16x16x32_bf16 v[100:103], v[210:213], v[190:193], v[100:103]
	v_mfma_f32_16x16x32_bf16 v[68:71], v[218:221], v[190:193], v[68:71]
	v_mfma_f32_16x16x32_bf16 v[96:99], v[210:213], v[202:205], v[96:99]
	v_mfma_f32_16x16x32_bf16 v[64:67], v[218:221], v[202:205], v[64:67]
	v_mfma_f32_16x16x32_bf16 v[116:119], v[214:217], v[178:181], v[116:119]
	v_mfma_f32_16x16x32_bf16 v[84:87], v[238:241], v[178:181], v[84:87]
	v_mfma_f32_16x16x32_bf16 v[104:107], v[214:217], v[186:189], v[104:107]
	v_mfma_f32_16x16x32_bf16 v[72:75], v[238:241], v[186:189], v[72:75]
	v_mfma_f32_16x16x32_bf16 v[100:103], v[214:217], v[198:201], v[100:103]
	v_mfma_f32_16x16x32_bf16 v[68:71], v[238:241], v[198:201], v[68:71]
	v_mfma_f32_16x16x32_bf16 v[96:99], v[214:217], v[206:209], v[96:99]
	v_mfma_f32_16x16x32_bf16 v[64:67], v[238:241], v[206:209], v[64:67]
	s_setprio 0
	s_mov_b32 m0, s64
	v_lshl_add_u64 v[152:153], v[222:223], 0, s[78:79]
	s_barrier
	ds_read_b128 v[144:147], v197 offset:49152
	ds_read_b128 v[178:181], v197 offset:50176
	ds_read_b128 v[182:185], v197 offset:51200
	ds_read_b128 v[186:189], v197 offset:52224
	ds_read_b128 v[190:193], v197 offset:53248
	ds_read_b128 v[198:201], v197 offset:54272
	ds_read_b128 v[202:205], v197 offset:55296
	ds_read_b128 v[206:209], v197 offset:56320
	global_load_lds_dwordx4 v[152:153], off
	v_lshl_add_u64 v[152:153], v[232:233], 0, s[78:79]
	s_mov_b32 m0, s65
	s_nop 0
	global_load_lds_dwordx4 v[152:153], off
	s_barrier
; #define PG8_STAGE(bufoff, gbase, voff) do { _Pragma("unroll") for (int _i = 0; _i < 2; ++_i) \
;         __builtin_amdgcn_global_load_lds((const unsigned*)((const char*)(gbase) + (voff)[_i]), (LAS unsigned*)(lds + (bufoff) + ldsw + _i * 8192), 16, 0, 0); } while (0)
; #define PG8_MMA(ai, bj, At, Bt) do { __builtin_amdgcn_s_setprio(1); _Pragma("unroll") for (int m = 0; m < 4; ++m) _Pragma("unroll") for (int n = 0; n < 2; ++n) _Pragma("unroll") for (int k = 0; k < 2; ++k) \
;         acc[ai][bj][m][n] = __builtin_amdgcn_mfma_f32_16x16x32_bf16(Bt[n][k], At[m][k], acc[ai][bj][m][n], 0, 0, 0); __builtin_amdgcn_s_setprio(0); } while (0)
; #define PG8_WAIT_V(n) asm volatile("s_waitcnt vmcnt(" #n ")" ::: "memory")
; #define PG8_WAIT_L(n) asm volatile("s_waitcnt lgkmcnt(" #n ")" ::: "memory")
; #define PG8_BAR __builtin_amdgcn_s_barrier()
; #define PG8_SCHED __builtin_amdgcn_sched_barrier(0)
; template <class Epi, class Sched>
; __device__ __forceinline__ void gemm_phase(LAS unsigned char* lds, const Gemm g, const Sched& S, const Epi& E) {
;     ...
;             PG8_BAR; PG8_WAIT_L(0); PG8_MMA(1, 0, At, B0); PG8_BAR; PG8_SCHED;
;             PG8_STAGE(PG8_SB(1, 1), b3 + hstep, voffB);
;             PG8_WAIT_V(6); PG8_BAR; PG8_MMA(1, 1, At, B1); PG8_BAR;
	s_waitcnt lgkmcnt(0)
	s_setprio 1
	s_waitcnt lgkmcnt(0)
	v_mfma_f32_16x16x32_bf16 v[60:63], v[128:131], v[144:147], v[60:63]
	v_mfma_f32_16x16x32_bf16 v[28:31], v[136:139], v[144:147], v[28:31]
	v_mfma_f32_16x16x32_bf16 v[48:51], v[128:131], v[182:185], v[48:51]
	v_mfma_f32_16x16x32_bf16 v[16:19], v[136:139], v[182:185], v[16:19]
	v_mfma_f32_16x16x32_bf16 v[44:47], v[128:131], v[190:193], v[44:47]
	v_mfma_f32_16x16x32_bf16 v[12:15], v[136:139], v[190:193], v[12:15]
	v_mfma_f32_16x16x32_bf16 v[56:59], v[128:131], v[202:205], v[56:59]
	v_mfma_f32_16x16x32_bf16 v[24:27], v[136:139], v[202:205], v[24:27]
	v_mfma_f32_16x16x32_bf16 v[60:63], v[132:135], v[178:181], v[60:63]
	v_mfma_f32_16x16x32_bf16 v[28:31], v[140:143], v[178:181], v[28:31]
	v_mfma_f32_16x16x32_bf16 v[48:51], v[132:135], v[186:189], v[48:51]
	v_mfma_f32_16x16x32_bf16 v[16:19], v[140:143], v[186:189], v[16:19]
	v_mfma_f32_16x16x32_bf16 v[44:47], v[132:135], v[198:201], v[44:47]
	v_mfma_f32_16x16x32_bf16 v[12:15], v[140:143], v[198:201], v[12:15]
	v_mfma_f32_16x16x32_bf16 v[56:59], v[132:135], v[206:209], v[56:59]
	v_mfma_f32_16x16x32_bf16 v[24:27], v[140:143], v[206:209], v[24:27]
	s_setprio 0
	s_barrier
	s_add_u32 s10, s10, 0x40080
	s_addc_u32 s11, s11, 0
	s_add_i32 s48, s48, s55
	v_lshl_add_u64 v[128:129], s[10:11], 0, v[154:155]
	s_mov_b32 m0, s48
	s_nop 0
	global_load_lds_dwordx4 v[128:129], off
	v_lshl_add_u64 v[128:129], s[10:11], 0, v[148:149]
	s_add_i32 m0, s48, 0x2000
	s_nop 0
	global_load_lds_dwordx4 v[128:129], off
	s_waitcnt vmcnt(6)
	s_barrier
	s_setprio 1
	v_mfma_f32_16x16x32_bf16 v[52:55], v[210:213], v[144:147], v[52:55]
	v_mfma_f32_16x16x32_bf16 v[20:23], v[218:221], v[144:147], v[20:23]
	v_mfma_f32_16x16x32_bf16 v[40:43], v[210:213], v[182:185], v[40:43]
	v_mfma_f32_16x16x32_bf16 v[8:11], v[218:221], v[182:185], v[8:11]
	v_mfma_f32_16x16x32_bf16 v[36:39], v[210:213], v[190:193], v[36:39]
	v_mfma_f32_16x16x32_bf16 v[4:7], v[218:221], v[190:193], v[4:7]
	v_mfma_f32_16x16x32_bf16 v[32:35], v[210:213], v[202:205], v[32:35]
	v_mfma_f32_16x16x32_bf16 v[0:3], v[218:221], v[202:205], v[0:3]
	v_mfma_f32_16x16x32_bf16 v[52:55], v[214:217], v[178:181], v[52:55]
	v_mfma_f32_16x16x32_bf16 v[20:23], v[238:241], v[178:181], v[20:23]
	v_mfma_f32_16x16x32_bf16 v[40:43], v[214:217], v[186:189], v[40:43]
	v_mfma_f32_16x16x32_bf16 v[8:11], v[238:241], v[186:189], v[8:11]
	v_mfma_f32_16x16x32_bf16 v[36:39], v[214:217], v[198:201], v[36:39]
	v_mfma_f32_16x16x32_bf16 v[4:7], v[238:241], v[198:201], v[4:7]
	v_mfma_f32_16x16x32_bf16 v[32:35], v[214:217], v[206:209], v[32:35]
	v_mfma_f32_16x16x32_bf16 v[0:3], v[238:241], v[206:209], v[0:3]
	s_setprio 0
	s_add_i32 s50, s50, 2
	s_add_u32 s43, s43, 0x100
	s_addc_u32 s67, s67, 0
	s_add_u32 s8, s8, 0x100
	s_addc_u32 s9, s9, 0
	s_cmp_gt_u32 s50, 13
	s_barrier
	s_cbranch_scc0 .LBB0_77
;     __device__ __forceinline__ bool next(int i, Unit& u) const { if (i >= 4) return false; u.pm = pm; u.pn = i; return true; }
;     __device__ __forceinline__ void operator()(const f32x4 (&acc)[2][2][4][2], const Unit& uu, int wr, int wc, int fr, int fq) const {
;     ...
;         const int chan0 = 128 * u.pn + 32 * wc + 8 * fq;
;         const int lane = fq * 16 + fr;
;         const int srcU = (lane & 48) | ((fr + 15) & 15), srcD = (lane & 48) | ((fr + 1) & 15);
; #pragma unroll
;         for (int ai = 0; ai < 2; ++ai) {
;             const int Rg = u.pm * 256 + 128 * ai + 64 * wr;
;             const int gi = Rg >> 6;
; #pragma unroll
;             for (int n = 0; n < 2; ++n) {
;                 const f32x4 w0 = *(const f32x4*)(cw + chan0 + 4 * n), w1 = *(const f32x4*)(cw + FF + chan0 + 4 * n), w2 = *(const f32x4*)(cw + 2 * FF + chan0 + 4 * n), bb = *(const f32x4*)(cb + chan0 + 4 * n);
;                 f32x4 av[4], ptop, pbot;
; #pragma unroll
;                 for (int j = 0; j < 4; ++j) {
;                     float gv[4], ru[4], rd[4];
; #pragma unroll
;                     for (int m = 0; m < 4; ++m) { gv[m] = acc[ai][0][m][n][j];
;                         ru[m] = __int_as_float(__builtin_amdgcn_update_dpp(0, __float_as_int(gv[m]), 0x121, 0xf, 0xf, false));
;                         rd[m] = __int_as_float(__builtin_amdgcn_update_dpp(0, __float_as_int(gv[m]), 0x12f, 0xf, 0xf, false)); }
; #pragma unroll
;                     for (int m = 0; m < 4; ++m) {
;                         const float prev = (fr == 0) ? (m > 0 ? ru[m > 0 ? m - 1 : 0] : 0.f) : ru[m];
;                         const float next = (fr == 15) ? (m < 3 ? rd[m < 3 ? m + 1 : 3] : 0.f) : rd[m];
;                         const float pre = w0[j] * prev + w1[j] * gv[m] + w2[j] * next + bb[j];
;                         av[m][j] = gelu_tanh_mul(pre, acc[ai][1][m][n][j]);
;                         if (m == 0) ptop[j] = pre;
;                         if (m == 3) pbot[j] = pre;
;                     }
;                 }
;                 if (fr == 0) { const size_t eo = ((size_t)gi * 2) * FF + chan0 + 4 * n; *(f32x4*)(EP + eo) = ptop; *(f32x4*)(EG + eo) = acc[ai][0][0][n]; *(f32x4*)(EU + eo) = acc[ai][1][0][n]; }
	v_mov_b32_e32 v128, v195
	v_mov_b32_e32 v156, v194
	s_lshl_b32 s7, s12, 7
	s_or_b32 s7, s7, s71
	v_lshl_add_u32 v178, v128, 3, s7
	v_ashrrev_i32_e32 v179, 31, v178
	v_lshlrev_b64 v[140:141], 2, v[178:179]
	v_lshl_add_u64 v[182:183], s[30:31], 0, v[140:141]
	v_lshl_add_u64 v[188:189], s[36:37], 0, v[140:141]
	global_load_dwordx4 v[136:139], v[182:183], off
	global_load_dwordx4 v[128:131], v[188:189], off
	v_lshl_add_u64 v[186:187], s[38:39], 0, v[140:141]
	global_load_dwordx4 v[132:135], v[186:187], off
	v_lshl_add_u64 v[180:181], s[34:35], 0, v[140:141]
	global_load_dwordx4 v[140:143], v[180:181], off
	global_load_dwordx4 v[158:161], v[182:183], off offset:16
	global_load_dwordx4 v[162:165], v[188:189], off offset:16
	global_load_dwordx4 v[166:169], v[186:187], off offset:16
	global_load_dwordx4 v[170:173], v[180:181], off offset:16
	v_mov_b32_e32 v216, v155
	v_mov_b32_e32 v217, v155
	v_mov_b32_e32 v144, v155
	v_mov_b32_e32 v220, v155
	v_mov_b32_e32 v146, v155
	v_mov_b32_e32 v219, v155
	v_mov_b32_dpp v216, v124 row_ror:1 row_mask:0xf bank_mask:0xf
	v_mov_b32_dpp v217, v125 row_ror:1 row_mask:0xf bank_mask:0xf
	v_mov_b32_dpp v144, v125 row_ror:15 row_mask:0xf bank_mask:0xf
	v_mov_b32_dpp v220, v113 row_ror:15 row_mask:0xf bank_mask:0xf
	v_cmp_eq_u32_e64 s[8:9], 0, v156
	v_cmp_eq_u32_e64 s[10:11], 15, v156
	v_mov_b32_e32 v212, v155
	v_mov_b32_e32 v209, v155
	v_mov_b32_dpp v146, v124 row_ror:15 row_mask:0xf bank_mask:0xf
	v_mov_b32_dpp v219, v112 row_ror:15 row_mask:0xf bank_mask:0xf
	v_cndmask_b32_e64 v145, v217, 0, s[8:9]
	v_cndmask_b32_e64 v147, v144, v220, s[10:11]
	v_cndmask_b32_e64 v144, v216, 0, s[8:9]
	v_mov_b32_e32 v223, v155
	v_mov_b32_e32 v214, v155
	v_mov_b32_e32 v224, v155
	v_mov_b32_e32 v213, v155
	v_mov_b32_dpp v212, v126 row_ror:1 row_mask:0xf bank_mask:0xf
	v_mov_b32_dpp v209, v127 row_ror:1 row_mask:0xf bank_mask:0xf
	s_lshl_b32 s33, s6, 8
	v_cndmask_b32_e64 v146, v146, v219, s[10:11]
	v_mov_b32_dpp v223, v126 row_ror:15 row_mask:0xf bank_mask:0xf
	v_mov_b32_dpp v214, v114 row_ror:15 row_mask:0xf bank_mask:0xf
	v_mov_b32_dpp v224, v127 row_ror:15 row_mask:0xf bank_mask:0xf
	v_mov_b32_dpp v213, v115 row_ror:15 row_mask:0xf bank_mask:0xf
	s_add_i32 s33, s33, s62
	s_ashr_i32 s41, s33, 6
	v_mov_b32_e32 v203, v155
	v_mov_b32_e32 v205, v155
	v_mov_b32_e32 v207, v155
	v_mov_b32_e32 v192, v155
	v_mov_b32_e32 v210, v155
	v_mov_b32_e32 v204, v155
	v_mov_b32_e32 v206, v155
	v_mov_b32_e32 v208, v155
	v_mov_b32_e32 v193, v155
	v_mov_b32_e32 v211, v155
	v_mov_b32_e32 v157, v155
	v_mov_b32_e32 v199, v155
	v_mov_b32_e32 v201, v155
	v_mov_b32_e32 v221, v155
	v_mov_b32_e32 v202, v155
	v_mov_b32_e32 v198, v155
	v_mov_b32_e32 v200, v155
	v_mad_i64_i32 v[152:153], s[48:49], s41, v235, v[178:179]
	v_mov_b32_e32 v215, v155
	v_mov_b32_e32 v222, v155
	v_mov_b32_e32 v218, v155
	v_mov_b32_dpp v203, v112 row_ror:1 row_mask:0xf bank_mask:0xf
	v_mov_b32_dpp v205, v108 row_ror:1 row_mask:0xf bank_mask:0xf
	v_mov_b32_dpp v207, v108 row_ror:15 row_mask:0xf bank_mask:0xf
	v_mov_b32_dpp v192, v120 row_ror:1 row_mask:0xf bank_mask:0xf
	v_mov_b32_dpp v210, v120 row_ror:15 row_mask:0xf bank_mask:0xf
	v_mov_b32_dpp v204, v113 row_ror:1 row_mask:0xf bank_mask:0xf
	v_mov_b32_dpp v206, v109 row_ror:1 row_mask:0xf bank_mask:0xf
	v_mov_b32_dpp v208, v109 row_ror:15 row_mask:0xf bank_mask:0xf
	v_mov_b32_dpp v193, v121 row_ror:1 row_mask:0xf bank_mask:0xf
	v_mov_b32_dpp v211, v121 row_ror:15 row_mask:0xf bank_mask:0xf
	v_mov_b32_dpp v157, v114 row_ror:1 row_mask:0xf bank_mask:0xf
	v_mov_b32_dpp v199, v110 row_ror:1 row_mask:0xf bank_mask:0xf
	v_mov_b32_dpp v201, v110 row_ror:15 row_mask:0xf bank_mask:0xf
	v_mov_b32_dpp v221, v122 row_ror:1 row_mask:0xf bank_mask:0xf
	v_mov_b32_dpp v202, v122 row_ror:15 row_mask:0xf bank_mask:0xf
	v_mov_b32_dpp v198, v115 row_ror:1 row_mask:0xf bank_mask:0xf
	v_mov_b32_dpp v200, v111 row_ror:1 row_mask:0xf bank_mask:0xf
	v_cmp_ne_u32_e64 s[12:13], 0, v156
	v_cmp_ne_u32_e64 s[6:7], 15, v156
	v_mov_b32_dpp v215, v111 row_ror:15 row_mask:0xf bank_mask:0xf
	s_waitcnt vmcnt(0)
	v_pk_mul_f32 v[190:191], v[124:125], v[128:129]
	v_pk_mul_f32 v[184:185], v[126:127], v[130:131]
	v_pk_fma_f32 v[144:145], v[136:137], v[144:145], v[190:191]
	v_cndmask_b32_e64 v191, v224, v213, s[10:11]
	v_pk_fma_f32 v[144:145], v[132:133], v[146:147], v[144:145]
	v_cndmask_b32_e64 v147, v209, 0, s[8:9]
	v_cndmask_b32_e64 v146, v212, 0, s[8:9]
	v_cndmask_b32_e64 v190, v223, v214, s[10:11]
	v_pk_fma_f32 v[146:147], v[138:139], v[146:147], v[184:185]
	v_pk_add_f32 v[144:145], v[140:141], v[144:145]
	v_pk_fma_f32 v[146:147], v[134:135], v[190:191], v[146:147]
	v_mov_b32_dpp v222, v123 row_ror:1 row_mask:0xf bank_mask:0xf
	v_mov_b32_dpp v218, v123 row_ror:15 row_mask:0xf bank_mask:0xf
	v_pk_add_f32 v[146:147], v[142:143], v[146:147]
	v_lshlrev_b64 v[190:191], 2, v[152:153]
	s_and_saveexec_b64 s[48:49], s[8:9]
	s_cbranch_execz .LBB0_80
	v_lshl_add_u64 v[152:153], s[24:25], 0, v[190:191]
	v_lshl_add_u64 v[184:185], s[26:27], 0, v[190:191]
	v_lshl_add_u64 v[232:233], s[28:29], 0, v[190:191]
	global_store_dwordx4 v[152:153], v[144:147], off
	global_store_dwordx4 v[184:185], v[124:127], off
	global_store_dwordx4 v[232:233], v[116:119], off

;     __device__ __forceinline__ bool next(int i, Unit& u) const { if (i >= 4) return false; u.pm = pm; u.pn = i; return true; }
;     __device__ __forceinline__ void operator()(const f32x4 (&acc)[2][2][4][2], const Unit& uu, int wr, int wc, int fr, int fq) const {
;     ...
;                 const f32x4 w0 = *(const f32x4*)(cw + chan0 + 4 * n), w1 = *(const f32x4*)(cw + FF + chan0 + 4 * n), w2 = *(const f32x4*)(cw + 2 * FF + chan0 + 4 * n), bb = *(const f32x4*)(cb + chan0 + 4 * n);
;                 f32x4 av[4], ptop, pbot;
; #pragma unroll
;                 for (int j = 0; j < 4; ++j) {
;                     float gv[4], ru[4], rd[4];
; #pragma unroll
;                     for (int m = 0; m < 4; ++m) { gv[m] = acc[ai][0][m][n][j];
;                         ru[m] = __int_as_float(__builtin_amdgcn_update_dpp(0, __float_as_int(gv[m]), 0x121, 0xf, 0xf, false));
;                         rd[m] = __int_as_float(__builtin_amdgcn_update_dpp(0, __float_as_int(gv[m]), 0x12f, 0xf, 0xf, false)); }
; #pragma unroll
;                     for (int m = 0; m < 4; ++m) {
;                         const float prev = (fr == 0) ? (m > 0 ? ru[m > 0 ? m - 1 : 0] : 0.f) : ru[m];
;                         const float next = (fr == 15) ? (m < 3 ? rd[m < 3 ? m + 1 : 3] : 0.f) : rd[m];
;                         const float pre = w0[j] * prev + w1[j] * gv[m] + w2[j] * next + bb[j];
;                         av[m][j] = gelu_tanh_mul(pre, acc[ai][1][m][n][j]);
;                         if (m == 0) ptop[j] = pre;
;                         if (m == 3) pbot[j] = pre;
;                     }
;                 }
;                 if (fr == 0) { const size_t eo = ((size_t)gi * 2) * FF + chan0 + 4 * n; *(f32x4*)(EP + eo) = ptop; *(f32x4*)(EG + eo) = acc[ai][0][0][n]; *(f32x4*)(EU + eo) = acc[ai][1][0][n]; }
;                 if (fr == 15) { const size_t eo = ((size_t)gi * 2 + 1) * FF + chan0 + 4 * n; *(f32x4*)(EP + eo) = pbot; *(f32x4*)(EG + eo) = acc[ai][0][3][n]; *(f32x4*)(EU + eo) = acc[ai][1][3][n]; }
.LBB0_86:
	s_or_b64 exec, exec, s[48:49]
	v_mov_b32_e32 v96, v158
	v_mov_b32_e32 v97, v159
	v_mov_b32_e32 v98, v160
	v_mov_b32_e32 v99, v161
	v_mov_b32_e32 v100, v162
	v_mov_b32_e32 v101, v163
	v_mov_b32_e32 v102, v164
	v_mov_b32_e32 v103, v165
	v_mov_b32_e32 v104, v166
	v_mov_b32_e32 v105, v167
	v_mov_b32_e32 v106, v168
	v_mov_b32_e32 v107, v169
	v_mov_b32_e32 v108, v170
	v_mov_b32_e32 v109, v171
	v_mov_b32_e32 v110, v172
	v_mov_b32_e32 v111, v173
	v_mov_b32_e32 v127, v155
	global_load_dwordx4 v[158:161], v[182:183], off
	global_load_dwordx4 v[162:165], v[188:189], off
	global_load_dwordx4 v[166:169], v[186:187], off
	global_load_dwordx4 v[170:173], v[180:181], off
	v_mov_b32_e32 v133, v155
	v_mov_b32_dpp v127, v92 row_ror:1 row_mask:0xf bank_mask:0xf
	v_cndmask_b32_e64 v112, v127, 0, s[8:9]
	v_mov_b32_dpp v133, v93 row_ror:1 row_mask:0xf bank_mask:0xf
	v_cndmask_b32_e64 v113, v133, 0, s[8:9]
	v_mov_b32_e32 v114, v155
	v_mov_b32_e32 v130, v155
	v_mov_b32_e32 v115, v155
	v_mov_b32_e32 v135, v155
	v_mov_b32_e32 v145, v155
	v_mov_b32_dpp v114, v92 row_ror:15 row_mask:0xf bank_mask:0xf
	v_mov_b32_dpp v130, v80 row_ror:15 row_mask:0xf bank_mask:0xf
	v_mov_b32_dpp v115, v93 row_ror:15 row_mask:0xf bank_mask:0xf
	v_mov_b32_dpp v135, v81 row_ror:15 row_mask:0xf bank_mask:0xf
	v_mov_b32_e32 v201, v155
	v_mov_b32_e32 v142, v155
	v_mov_b32_dpp v145, v95 row_ror:1 row_mask:0xf bank_mask:0xf
	v_mov_b32_e32 v202, v155
	v_mov_b32_e32 v147, v155
	v_cndmask_b32_e64 v137, v115, v135, s[10:11]
	v_cndmask_b32_e64 v136, v114, v130, s[10:11]
	v_mov_b32_dpp v201, v94 row_ror:15 row_mask:0xf bank_mask:0xf
	v_mov_b32_dpp v142, v82 row_ror:15 row_mask:0xf bank_mask:0xf
	v_mov_b32_dpp v202, v95 row_ror:15 row_mask:0xf bank_mask:0xf
	v_mov_b32_dpp v147, v83 row_ror:15 row_mask:0xf bank_mask:0xf
	v_cndmask_b32_e64 v153, v145, 0, s[8:9]
	v_cndmask_b32_e64 v203, v202, v147, s[10:11]
	v_cndmask_b32_e64 v202, v201, v142, s[10:11]
	v_mov_b32_e32 v124, v155
	v_mov_b32_e32 v125, v155
	v_mov_b32_e32 v126, v155
	v_mov_b32_e32 v157, v155
	v_mov_b32_e32 v128, v155
	v_mov_b32_e32 v129, v155
	v_mov_b32_e32 v131, v155
	v_mov_b32_e32 v132, v155
	v_mov_b32_e32 v198, v155
	v_mov_b32_e32 v134, v155
	v_mov_b32_e32 v199, v155
	v_mov_b32_e32 v140, v155
	v_mov_b32_e32 v141, v155
	v_mov_b32_e32 v143, v155
	v_mov_b32_e32 v144, v155
	v_mov_b32_e32 v200, v155
	v_mov_b32_e32 v146, v155
	v_mov_b32_dpp v124, v80 row_ror:1 row_mask:0xf bank_mask:0xf
	v_mov_b32_dpp v125, v76 row_ror:1 row_mask:0xf bank_mask:0xf
	v_mov_b32_dpp v126, v76 row_ror:15 row_mask:0xf bank_mask:0xf
	v_mov_b32_dpp v157, v88 row_ror:1 row_mask:0xf bank_mask:0xf
	v_mov_b32_dpp v128, v88 row_ror:15 row_mask:0xf bank_mask:0xf
	v_mov_b32_dpp v129, v81 row_ror:1 row_mask:0xf bank_mask:0xf
	v_mov_b32_dpp v131, v77 row_ror:1 row_mask:0xf bank_mask:0xf
	v_mov_b32_dpp v132, v77 row_ror:15 row_mask:0xf bank_mask:0xf
	v_mov_b32_dpp v198, v89 row_ror:1 row_mask:0xf bank_mask:0xf
	v_mov_b32_dpp v134, v89 row_ror:15 row_mask:0xf bank_mask:0xf
	v_mov_b32_dpp v199, v90 row_ror:1 row_mask:0xf bank_mask:0xf
	v_mov_b32_dpp v140, v90 row_ror:15 row_mask:0xf bank_mask:0xf
	v_mov_b32_dpp v141, v83 row_ror:1 row_mask:0xf bank_mask:0xf
	v_mov_b32_dpp v143, v79 row_ror:1 row_mask:0xf bank_mask:0xf
	v_mov_b32_dpp v144, v79 row_ror:15 row_mask:0xf bank_mask:0xf
	v_mov_b32_dpp v200, v91 row_ror:1 row_mask:0xf bank_mask:0xf
	v_mov_b32_dpp v146, v91 row_ror:15 row_mask:0xf bank_mask:0xf
	v_pk_mul_f32 v[138:139], v[92:93], v[100:101]
	s_nop 0
	v_pk_fma_f32 v[112:113], v[96:97], v[112:113], v[138:139]
	v_mov_b32_e32 v139, v155
	v_pk_mul_f32 v[114:115], v[94:95], v[102:103]
	v_mov_b32_e32 v138, v155
	v_mov_b32_dpp v139, v94 row_ror:1 row_mask:0xf bank_mask:0xf
	v_cndmask_b32_e64 v152, v139, 0, s[8:9]
	v_pk_fma_f32 v[114:115], v[98:99], v[152:153], v[114:115]
	v_pk_fma_f32 v[112:113], v[104:105], v[136:137], v[112:113]
	v_mov_b32_e32 v136, v155
	v_mov_b32_e32 v137, v155
	v_pk_fma_f32 v[114:115], v[106:107], v[202:203], v[114:115]
	v_pk_add_f32 v[112:113], v[108:109], v[112:113]
	v_mov_b32_dpp v136, v82 row_ror:1 row_mask:0xf bank_mask:0xf
	v_mov_b32_dpp v137, v78 row_ror:1 row_mask:0xf bank_mask:0xf
	v_mov_b32_dpp v138, v78 row_ror:15 row_mask:0xf bank_mask:0xf
	v_pk_add_f32 v[114:115], v[110:111], v[114:115]
	s_and_saveexec_b64 s[48:49], s[8:9]
	s_cbranch_execz .LBB0_88
	v_or_b32_e32 v190, 16, v190
	v_lshl_add_u64 v[152:153], s[24:25], 0, v[190:191]
	v_lshl_add_u64 v[202:203], s[26:27], 0, v[190:191]
	v_lshl_add_u64 v[190:191], s[28:29], 0, v[190:191]
	global_store_dwordx4 v[152:153], v[112:115], off
	global_store_dwordx4 v[202:203], v[92:95], off
	global_store_dwordx4 v[190:191], v[84:87], off

;     __device__ __forceinline__ bool next(int i, Unit& u) const { if (i >= 4) return false; u.pm = pm; u.pn = i; return true; }
;     __device__ __forceinline__ void operator()(const f32x4 (&acc)[2][2][4][2], const Unit& uu, int wr, int wc, int fr, int fq) const {
;     ...
;         for (int ai = 0; ai < 2; ++ai) {
;             const int Rg = u.pm * 256 + 128 * ai + 64 * wr;
;             const int gi = Rg >> 6;
; #pragma unroll
;             for (int n = 0; n < 2; ++n) {
;                 const f32x4 w0 = *(const f32x4*)(cw + chan0 + 4 * n), w1 = *(const f32x4*)(cw + FF + chan0 + 4 * n), w2 = *(const f32x4*)(cw + 2 * FF + chan0 + 4 * n), bb = *(const f32x4*)(cb + chan0 + 4 * n);
;                 f32x4 av[4], ptop, pbot;
; #pragma unroll
;                 for (int j = 0; j < 4; ++j) {
;                     float gv[4], ru[4], rd[4];
; #pragma unroll
;                     for (int m = 0; m < 4; ++m) { gv[m] = acc[ai][0][m][n][j];
;                         ru[m] = __int_as_float(__builtin_amdgcn_update_dpp(0, __float_as_int(gv[m]), 0x121, 0xf, 0xf, false));
;                         rd[m] = __int_as_float(__builtin_amdgcn_update_dpp(0, __float_as_int(gv[m]), 0x12f, 0xf, 0xf, false)); }
; #pragma unroll
;                     for (int m = 0; m < 4; ++m) {
;                         const float prev = (fr == 0) ? (m > 0 ? ru[m > 0 ? m - 1 : 0] : 0.f) : ru[m];
;                         const float next = (fr == 15) ? (m < 3 ? rd[m < 3 ? m + 1 : 3] : 0.f) : rd[m];
;                         const float pre = w0[j] * prev + w1[j] * gv[m] + w2[j] * next + bb[j];
;                         av[m][j] = gelu_tanh_mul(pre, acc[ai][1][m][n][j]);
;                         if (m == 0) ptop[j] = pre;
;                         if (m == 3) pbot[j] = pre;
;                     }
;                 }
;                 if (fr == 0) { const size_t eo = ((size_t)gi * 2) * FF + chan0 + 4 * n; *(f32x4*)(EP + eo) = ptop; *(f32x4*)(EG + eo) = acc[ai][0][0][n]; *(f32x4*)(EU + eo) = acc[ai][1][0][n]; }
;                 if (fr == 15) { const size_t eo = ((size_t)gi * 2 + 1) * FF + chan0 + 4 * n; *(f32x4*)(EP + eo) = pbot; *(f32x4*)(EG + eo) = acc[ai][0][3][n]; *(f32x4*)(EU + eo) = acc[ai][1][3][n]; }
.LBB0_94:
	s_or_b64 exec, exec, s[48:49]
	s_waitcnt vmcnt(10)
	v_mov_b32_e32 v64, v158
	v_mov_b32_e32 v65, v159
	v_mov_b32_e32 v66, v160
	v_mov_b32_e32 v67, v161
	v_mov_b32_e32 v68, v162
	v_mov_b32_e32 v69, v163
	v_mov_b32_e32 v70, v164
	v_mov_b32_e32 v71, v165
	v_mov_b32_e32 v72, v166
	v_mov_b32_e32 v73, v167
	v_mov_b32_e32 v74, v168
	v_mov_b32_e32 v75, v169
	v_mov_b32_e32 v76, v170
	v_mov_b32_e32 v77, v171
	v_mov_b32_e32 v78, v172
	v_mov_b32_e32 v79, v173
	global_load_dwordx4 v[158:161], v[182:183], off offset:16
	global_load_dwordx4 v[162:165], v[188:189], off offset:16
	global_load_dwordx4 v[166:169], v[186:187], off offset:16
	global_load_dwordx4 v[170:173], v[180:181], off offset:16
	v_mov_b32_e32 v91, v155
	v_mov_b32_e32 v97, v155
	v_mov_b32_e32 v82, v155
	v_mov_b32_dpp v91, v60 row_ror:1 row_mask:0xf bank_mask:0xf
	v_mov_b32_dpp v97, v61 row_ror:1 row_mask:0xf bank_mask:0xf
	v_cndmask_b32_e64 v81, v97, 0, s[8:9]
	v_cndmask_b32_e64 v80, v91, 0, s[8:9]
	v_mov_b32_e32 v94, v155
	v_mov_b32_e32 v83, v155
	v_mov_b32_e32 v99, v155
	v_mov_b32_e32 v109, v155
	v_mov_b32_dpp v82, v60 row_ror:15 row_mask:0xf bank_mask:0xf
	v_mov_b32_dpp v94, v48 row_ror:15 row_mask:0xf bank_mask:0xf
	v_mov_b32_dpp v83, v61 row_ror:15 row_mask:0xf bank_mask:0xf
	v_mov_b32_dpp v99, v49 row_ror:15 row_mask:0xf bank_mask:0xf
	v_mov_b32_e32 v118, v155
	v_mov_b32_e32 v106, v155
	v_mov_b32_dpp v109, v63 row_ror:1 row_mask:0xf bank_mask:0xf
	v_mov_b32_e32 v119, v155
	v_mov_b32_e32 v111, v155
	s_addk_i32 s33, 0x80
	v_cndmask_b32_e64 v101, v83, v99, s[10:11]
	v_cndmask_b32_e64 v100, v82, v94, s[10:11]
	v_mov_b32_dpp v118, v62 row_ror:15 row_mask:0xf bank_mask:0xf
	v_mov_b32_dpp v106, v50 row_ror:15 row_mask:0xf bank_mask:0xf
	v_mov_b32_dpp v119, v63 row_ror:15 row_mask:0xf bank_mask:0xf
	v_mov_b32_dpp v111, v51 row_ror:15 row_mask:0xf bank_mask:0xf
	v_cndmask_b32_e64 v115, v109, 0, s[8:9]
	s_ashr_i32 s41, s33, 6
	v_cndmask_b32_e64 v119, v119, v111, s[10:11]
	v_cndmask_b32_e64 v118, v118, v106, s[10:11]
	v_mad_i64_i32 v[84:85], s[48:49], s41, v235, v[178:179]
	v_mov_b32_e32 v88, v155
	v_mov_b32_e32 v89, v155
	v_mov_b32_e32 v90, v155
	v_mov_b32_e32 v86, v155
	v_mov_b32_e32 v92, v155
	v_mov_b32_e32 v93, v155
	v_mov_b32_e32 v95, v155
	v_mov_b32_e32 v96, v155
	v_mov_b32_e32 v87, v155
	v_mov_b32_e32 v98, v155
	v_mov_b32_e32 v112, v155
	v_mov_b32_e32 v104, v155
	v_mov_b32_e32 v105, v155
	v_mov_b32_e32 v107, v155
	v_mov_b32_e32 v108, v155
	v_mov_b32_e32 v113, v155
	v_mov_b32_e32 v110, v155
	v_mov_b32_dpp v88, v48 row_ror:1 row_mask:0xf bank_mask:0xf
	v_mov_b32_dpp v89, v44 row_ror:1 row_mask:0xf bank_mask:0xf
	v_mov_b32_dpp v90, v44 row_ror:15 row_mask:0xf bank_mask:0xf
	v_mov_b32_dpp v86, v56 row_ror:1 row_mask:0xf bank_mask:0xf
	v_mov_b32_dpp v92, v56 row_ror:15 row_mask:0xf bank_mask:0xf
	v_mov_b32_dpp v93, v49 row_ror:1 row_mask:0xf bank_mask:0xf
	v_mov_b32_dpp v95, v45 row_ror:1 row_mask:0xf bank_mask:0xf
	v_mov_b32_dpp v96, v45 row_ror:15 row_mask:0xf bank_mask:0xf
	v_mov_b32_dpp v87, v57 row_ror:1 row_mask:0xf bank_mask:0xf
	v_mov_b32_dpp v98, v57 row_ror:15 row_mask:0xf bank_mask:0xf
	v_mov_b32_dpp v112, v58 row_ror:1 row_mask:0xf bank_mask:0xf
	v_mov_b32_dpp v104, v58 row_ror:15 row_mask:0xf bank_mask:0xf
	v_mov_b32_dpp v105, v51 row_ror:1 row_mask:0xf bank_mask:0xf
	v_mov_b32_dpp v107, v47 row_ror:1 row_mask:0xf bank_mask:0xf
	v_mov_b32_dpp v108, v47 row_ror:15 row_mask:0xf bank_mask:0xf
	v_mov_b32_dpp v113, v59 row_ror:1 row_mask:0xf bank_mask:0xf
	v_mov_b32_dpp v110, v59 row_ror:15 row_mask:0xf bank_mask:0xf
	v_lshlrev_b64 v[84:85], 2, v[84:85]
	v_pk_mul_f32 v[102:103], v[60:61], v[68:69]
	s_nop 0
	v_pk_fma_f32 v[80:81], v[64:65], v[80:81], v[102:103]
	v_mov_b32_e32 v103, v155
	v_pk_mul_f32 v[82:83], v[62:63], v[70:71]
	v_pk_fma_f32 v[80:81], v[72:73], v[100:101], v[80:81]
	v_mov_b32_dpp v103, v62 row_ror:1 row_mask:0xf bank_mask:0xf
	v_cndmask_b32_e64 v114, v103, 0, s[8:9]
	v_pk_fma_f32 v[82:83], v[66:67], v[114:115], v[82:83]
	v_mov_b32_e32 v100, v155
	v_mov_b32_e32 v101, v155
	v_mov_b32_e32 v102, v155
	v_pk_fma_f32 v[82:83], v[74:75], v[118:119], v[82:83]
	v_pk_add_f32 v[80:81], v[76:77], v[80:81]
	v_mov_b32_dpp v100, v50 row_ror:1 row_mask:0xf bank_mask:0xf
	v_mov_b32_dpp v101, v46 row_ror:1 row_mask:0xf bank_mask:0xf
	v_mov_b32_dpp v102, v46 row_ror:15 row_mask:0xf bank_mask:0xf
	v_pk_add_f32 v[82:83], v[78:79], v[82:83]
	s_and_saveexec_b64 s[48:49], s[8:9]
	s_cbranch_execz .LBB0_96
	v_lshl_add_u64 v[114:115], s[24:25], 0, v[84:85]
	v_lshl_add_u64 v[118:119], s[26:27], 0, v[84:85]
	v_lshl_add_u64 v[120:121], s[28:29], 0, v[84:85]
	global_store_dwordx4 v[114:115], v[80:83], off
	global_store_dwordx4 v[118:119], v[60:63], off
	global_store_dwordx4 v[120:121], v[52:55], off

;     __device__ __forceinline__ bool next(int i, Unit& u) const { if (i >= 4) return false; u.pm = pm; u.pn = i; return true; }
;     __device__ __forceinline__ void operator()(const f32x4 (&acc)[2][2][4][2], const Unit& uu, int wr, int wc, int fr, int fq) const {
;     ...
;             for (int n = 0; n < 2; ++n) {
;                 const f32x4 w0 = *(const f32x4*)(cw + chan0 + 4 * n), w1 = *(const f32x4*)(cw + FF + chan0 + 4 * n), w2 = *(const f32x4*)(cw + 2 * FF + chan0 + 4 * n), bb = *(const f32x4*)(cb + chan0 + 4 * n);
;                 f32x4 av[4], ptop, pbot;
; #pragma unroll
;                 for (int j = 0; j < 4; ++j) {
;                     float gv[4], ru[4], rd[4];
; #pragma unroll
;                     for (int m = 0; m < 4; ++m) { gv[m] = acc[ai][0][m][n][j];
;                         ru[m] = __int_as_float(__builtin_amdgcn_update_dpp(0, __float_as_int(gv[m]), 0x121, 0xf, 0xf, false));
;                         rd[m] = __int_as_float(__builtin_amdgcn_update_dpp(0, __float_as_int(gv[m]), 0x12f, 0xf, 0xf, false)); }
; #pragma unroll
;                     for (int m = 0; m < 4; ++m) {
;                         const float prev = (fr == 0) ? (m > 0 ? ru[m > 0 ? m - 1 : 0] : 0.f) : ru[m];
;                         const float next = (fr == 15) ? (m < 3 ? rd[m < 3 ? m + 1 : 3] : 0.f) : rd[m];
;                         const float pre = w0[j] * prev + w1[j] * gv[m] + w2[j] * next + bb[j];
;                         av[m][j] = gelu_tanh_mul(pre, acc[ai][1][m][n][j]);
;                         if (m == 0) ptop[j] = pre;
;                         if (m == 3) pbot[j] = pre;
;                     }
;                 }
;                 if (fr == 0) { const size_t eo = ((size_t)gi * 2) * FF + chan0 + 4 * n; *(f32x4*)(EP + eo) = ptop; *(f32x4*)(EG + eo) = acc[ai][0][0][n]; *(f32x4*)(EU + eo) = acc[ai][1][0][n]; }
;                 if (fr == 15) { const size_t eo = ((size_t)gi * 2 + 1) * FF + chan0 + 4 * n; *(f32x4*)(EP + eo) = pbot; *(f32x4*)(EG + eo) = acc[ai][0][3][n]; *(f32x4*)(EU + eo) = acc[ai][1][3][n]; }
.LBB0_102:
	s_or_b64 exec, exec, s[48:49]
	s_waitcnt vmcnt(10)
	v_mov_b32_e32 v32, v158
	v_mov_b32_e32 v33, v159
	v_mov_b32_e32 v34, v160
	v_mov_b32_e32 v35, v161
	v_mov_b32_e32 v36, v162
	v_mov_b32_e32 v37, v163
	v_mov_b32_e32 v38, v164
	v_mov_b32_e32 v39, v165
	v_mov_b32_e32 v40, v166
	v_mov_b32_e32 v41, v167
	v_mov_b32_e32 v42, v168
	v_mov_b32_e32 v43, v169
	v_mov_b32_e32 v44, v170
	v_mov_b32_e32 v45, v171
	v_mov_b32_e32 v46, v172
	v_mov_b32_e32 v47, v173
	v_mov_b32_e32 v61, v155
	v_mov_b32_e32 v67, v155
	v_mov_b32_e32 v50, v155
	v_mov_b32_dpp v61, v28 row_ror:1 row_mask:0xf bank_mask:0xf
	v_mov_b32_dpp v67, v29 row_ror:1 row_mask:0xf bank_mask:0xf
	v_cndmask_b32_e64 v49, v67, 0, s[8:9]
	v_cndmask_b32_e64 v48, v61, 0, s[8:9]
	v_mov_b32_e32 v64, v155
	v_mov_b32_e32 v51, v155
	v_mov_b32_e32 v69, v155
	v_mov_b32_e32 v79, v155
	v_mov_b32_dpp v50, v28 row_ror:15 row_mask:0xf bank_mask:0xf
	v_mov_b32_dpp v64, v16 row_ror:15 row_mask:0xf bank_mask:0xf
	v_mov_b32_dpp v51, v29 row_ror:15 row_mask:0xf bank_mask:0xf
	v_mov_b32_dpp v69, v17 row_ror:15 row_mask:0xf bank_mask:0xf
	v_mov_b32_e32 v92, v155
	v_mov_b32_e32 v76, v155
	v_mov_b32_dpp v79, v31 row_ror:1 row_mask:0xf bank_mask:0xf
	v_mov_b32_e32 v93, v155
	v_mov_b32_e32 v81, v155
	v_cndmask_b32_e64 v71, v51, v69, s[10:11]
	v_cndmask_b32_e64 v70, v50, v64, s[10:11]
	v_mov_b32_dpp v92, v30 row_ror:15 row_mask:0xf bank_mask:0xf
	v_mov_b32_dpp v76, v18 row_ror:15 row_mask:0xf bank_mask:0xf
	v_mov_b32_dpp v93, v31 row_ror:15 row_mask:0xf bank_mask:0xf
	v_mov_b32_dpp v81, v19 row_ror:15 row_mask:0xf bank_mask:0xf
	v_cndmask_b32_e64 v91, v79, 0, s[8:9]
	v_cndmask_b32_e64 v93, v93, v81, s[10:11]
	v_cndmask_b32_e64 v92, v92, v76, s[10:11]
	v_mov_b32_e32 v58, v155
	v_mov_b32_e32 v59, v155
	v_mov_b32_e32 v60, v155
	v_mov_b32_e32 v82, v155
	v_mov_b32_e32 v62, v155
	v_mov_b32_e32 v63, v155
	v_mov_b32_e32 v65, v155
	v_mov_b32_e32 v66, v155
	v_mov_b32_e32 v83, v155
	v_mov_b32_e32 v68, v155
	v_mov_b32_e32 v88, v155
	v_mov_b32_e32 v74, v155
	v_mov_b32_e32 v75, v155
	v_mov_b32_e32 v77, v155
	v_mov_b32_e32 v78, v155
	v_mov_b32_e32 v89, v155
	v_mov_b32_e32 v80, v155
	v_mov_b32_dpp v58, v16 row_ror:1 row_mask:0xf bank_mask:0xf
	v_mov_b32_dpp v59, v12 row_ror:1 row_mask:0xf bank_mask:0xf
	v_mov_b32_dpp v60, v12 row_ror:15 row_mask:0xf bank_mask:0xf
	v_mov_b32_dpp v82, v24 row_ror:1 row_mask:0xf bank_mask:0xf
	v_mov_b32_dpp v62, v24 row_ror:15 row_mask:0xf bank_mask:0xf
	v_mov_b32_dpp v63, v17 row_ror:1 row_mask:0xf bank_mask:0xf
	v_mov_b32_dpp v65, v13 row_ror:1 row_mask:0xf bank_mask:0xf
	v_mov_b32_dpp v66, v13 row_ror:15 row_mask:0xf bank_mask:0xf
	v_mov_b32_dpp v83, v25 row_ror:1 row_mask:0xf bank_mask:0xf
	v_mov_b32_dpp v68, v25 row_ror:15 row_mask:0xf bank_mask:0xf
	v_mov_b32_dpp v88, v26 row_ror:1 row_mask:0xf bank_mask:0xf
	v_mov_b32_dpp v74, v26 row_ror:15 row_mask:0xf bank_mask:0xf
	v_mov_b32_dpp v75, v19 row_ror:1 row_mask:0xf bank_mask:0xf
	v_mov_b32_dpp v77, v15 row_ror:1 row_mask:0xf bank_mask:0xf
	v_mov_b32_dpp v78, v15 row_ror:15 row_mask:0xf bank_mask:0xf
	v_mov_b32_dpp v89, v27 row_ror:1 row_mask:0xf bank_mask:0xf
	v_mov_b32_dpp v80, v27 row_ror:15 row_mask:0xf bank_mask:0xf
	v_pk_mul_f32 v[72:73], v[28:29], v[36:37]
	s_nop 0
	v_pk_fma_f32 v[48:49], v[32:33], v[48:49], v[72:73]
	v_mov_b32_e32 v73, v155
	v_pk_mul_f32 v[50:51], v[30:31], v[38:39]
	v_pk_fma_f32 v[48:49], v[40:41], v[70:71], v[48:49]
	v_mov_b32_dpp v73, v30 row_ror:1 row_mask:0xf bank_mask:0xf
	v_cndmask_b32_e64 v90, v73, 0, s[8:9]
	v_pk_fma_f32 v[50:51], v[34:35], v[90:91], v[50:51]
	v_mov_b32_e32 v70, v155
	v_mov_b32_e32 v71, v155
	v_mov_b32_e32 v72, v155
	v_pk_fma_f32 v[50:51], v[42:43], v[92:93], v[50:51]
	v_pk_add_f32 v[48:49], v[44:45], v[48:49]
	v_mov_b32_dpp v70, v18 row_ror:1 row_mask:0xf bank_mask:0xf
	v_mov_b32_dpp v71, v14 row_ror:1 row_mask:0xf bank_mask:0xf
	v_mov_b32_dpp v72, v14 row_ror:15 row_mask:0xf bank_mask:0xf
	v_pk_add_f32 v[50:51], v[46:47], v[50:51]
	s_and_saveexec_b64 s[48:49], s[8:9]
	s_cbranch_execz .LBB0_104
	v_or_b32_e32 v84, 16, v84
	v_lshl_add_u64 v[90:91], s[24:25], 0, v[84:85]
	v_lshl_add_u64 v[92:93], s[26:27], 0, v[84:85]
	v_lshl_add_u64 v[84:85], s[28:29], 0, v[84:85]
	global_store_dwordx4 v[90:91], v[48:51], off
	global_store_dwordx4 v[92:93], v[28:31], off
	global_store_dwordx4 v[84:85], v[20:23], off

; #define LAS __attribute__((address_space(3)))
; template <bool KLDS>
; __device__ __forceinline__ void attn_step(const bf16x8 (&kf)[4], LAS const unsigned char* kb, const bf16x8 (&vf)[2][2], const bf16x8 (&qf)[4], f32x16& o0, f32x16& o1, float& m, float& l, int lane, int maskmode) {
;     const int ql = lane & 31, h = lane >> 5;
;     f32x16 S;
; #pragma unroll
;     for (int i = 0; i < 16; ++i) S[i] = 0.f;
; #pragma unroll
;     for (int s = 0; s < 4; ++s) {
;         if (KLDS) { const int pc = (2 * s + h) ^ ((ql >> 1) & 7); const bf16x8 k1 = *(const LAS bf16x8*)(kb + ql * 128 + pc * 16); S = __builtin_amdgcn_mfma_f32_32x32x16_bf16(k1, qf[s], S, 0, 0, 0); }
;         else S = __builtin_amdgcn_mfma_f32_32x32x16_bf16(kf[s], qf[s], S, 0, 0, 0);
;     }
;     if (maskmode) {
; #pragma unroll
;         for (int i = 0; i < 16; ++i) { const int kr = (i & 3) + 8 * (i >> 2) + 4 * h; const bool ok = (maskmode == 1) ? (kr >= ql) : (kr <= ql); S[i] = ok ? S[i] : -1e30f; }
;     }
;     float tm = S[0];
; #pragma unroll
;     for (int i = 1; i < 16; ++i) tm = fmaxf(tm, S[i]);
;     tm = fmaxf(tm, __shfl_xor(tm, 32));
;     const float mn = fmaxf(m, tm), al = fexp2(m - mn); m = mn;
;     float ps = 0.f;
; #pragma unroll
;     for (int i = 0; i < 16; ++i) { S[i] = fexp2(S[i] - mn); ps += S[i]; }
;     l = l * al + ps;
; #pragma unroll
;     for (int i = 0; i < 16; ++i) { o0[i] *= al; o1[i] *= al; }
;     bf16x8 pf[2];
; #pragma unroll
;     for (int s2 = 0; s2 < 2; ++s2) {
;         u32x4 w; w.x = pk2n(S[8 * s2 + 0], S[8 * s2 + 1]); w.y = pk2n(S[8 * s2 + 2], S[8 * s2 + 3]); w.z = pk2n(S[8 * s2 + 4], S[8 * s2 + 5]); w.w = pk2n(S[8 * s2 + 6], S[8 * s2 + 7]);
;         pf[s2] = __builtin_bit_cast(bf16x8, w);
;     }
; #pragma unroll
;     for (int s2 = 0; s2 < 2; ++s2) {
;         o0 = __builtin_amdgcn_mfma_f32_32x32x16_bf16(vf[s2][0], pf[s2], o0, 0, 0, 0);
;         o1 = __builtin_amdgcn_mfma_f32_32x32x16_bf16(vf[s2][1], pf[s2], o1, 0, 0, 0);
;     }
; __device__ __forceinline__ void attnC_unit(const Args& a, int unit, LAS unsigned char* lds) {
;     ...
;             bf16x8 kf[4], vf[2][2];
;             load_kf(cur + j * 4096, kf, lane); load_vf(cur + 8192 + j * 4096, vf, lane);
; #pragma unroll
;             for (int e = 0; e < 2; ++e) attn_step<false>(kf, cur, vf, qf[e], o0[e], o1[e], m[e], l[e], lane, 0);
.LBB0_254:
	s_add_i32 s4, s2, 0xffffc000
	s_and_b32 s4, s4, 0x4000
	s_add_i32 s4, s4, 0
	v_add_u32_e32 v64, s4, v252
	v_add_u32_e32 v124, v64, v231
	ds_read_b128 v[126:129], v124
	v_add_u32_e32 v123, v64, v239
	ds_read_b128 v[130:133], v123
	v_add_u32_e32 v121, v64, v232
	v_add_u32_e32 v120, v64, v241
	ds_read_b128 v[138:141], v121
	ds_read_b128 v[142:145], v120
	v_add3_u32 v122, s4, v157, v156
	ds_read_b64_tr_b16 v[146:147], v122 offset:8192
	ds_read_b64_tr_b16 v[148:149], v122 offset:9216
	ds_read_b64_tr_b16 v[204:205], v122 offset:8256
	ds_read_b64_tr_b16 v[206:207], v122 offset:9280
	ds_read_b64_tr_b16 v[208:209], v122 offset:10240
	ds_read_b64_tr_b16 v[210:211], v122 offset:11264
	ds_read_b64_tr_b16 v[212:213], v122 offset:10304
	ds_read_b64_tr_b16 v[214:215], v122 offset:11328
	s_waitcnt lgkmcnt(11)
	v_mfma_f32_32x32x16_bf16 v[64:79], v[126:129], v[80:83], 0
	s_addk_i32 s2, 0x4000
	s_add_i32 s3, s3, 1
	v_lshl_add_u64 v[180:181], v[180:181], 0, s[18:19]
	s_cmp_lg_u32 s2, 0x84000
	s_waitcnt lgkmcnt(10)
	v_mfma_f32_32x32x16_bf16 v[64:79], v[130:133], v[84:87], v[64:79]
	s_waitcnt lgkmcnt(9)
	v_mfma_f32_32x32x16_bf16 v[64:79], v[138:141], v[88:91], v[64:79]
	s_waitcnt lgkmcnt(8)
	v_mfma_f32_32x32x16_bf16 v[64:79], v[142:145], v[92:95], v[64:79]
	s_nop 11
	v_max_f32_e32 v125, v65, v65
	v_max_f32_e32 v134, v64, v64
	v_max_f32_e32 v125, v134, v125
	v_max3_f32 v125, v125, v66, v67
	v_max3_f32 v125, v125, v68, v69
	v_max3_f32 v125, v125, v70, v71
	v_max3_f32 v125, v125, v72, v73
	v_max3_f32 v125, v125, v74, v75
	v_max3_f32 v125, v125, v76, v77
	v_max3_f32 v125, v125, v78, v79
	ds_bpermute_b32 v134, v248, v125
	s_waitcnt lgkmcnt(0)
	v_max3_f32 v202, v235, v125, v134
	v_sub_f32_e32 v64, v64, v202
	v_exp_f32_e32 v64, v64
	v_sub_f32_e32 v65, v65, v202
	v_exp_f32_e32 v65, v65
	v_sub_f32_e32 v66, v66, v202
	v_sub_f32_e32 v125, v235, v202
	v_exp_f32_e32 v66, v66
	v_sub_f32_e32 v67, v67, v202
	v_sub_f32_e32 v68, v68, v202
	v_sub_f32_e32 v69, v69, v202
	v_sub_f32_e32 v70, v70, v202
	v_sub_f32_e32 v71, v71, v202
	v_exp_f32_e32 v67, v67
	v_exp_f32_e32 v68, v68
	v_exp_f32_e32 v69, v69
	v_exp_f32_e32 v70, v70
	v_exp_f32_e32 v71, v71
	v_sub_f32_e32 v72, v72, v202
	v_exp_f32_e32 v154, v125
	v_add_f32_e32 v134, 0, v64
	v_exp_f32_e32 v199, v72
	v_sub_f32_e32 v72, v73, v202
	v_add_f32_e32 v134, v65, v134
	v_exp_f32_e32 v197, v72
	v_sub_f32_e32 v72, v74, v202
	v_add_f32_e32 v134, v66, v134
	v_exp_f32_e32 v193, v72
	v_sub_f32_e32 v72, v75, v202
	v_add_f32_e32 v134, v67, v134
	v_exp_f32_e32 v191, v72
	v_sub_f32_e32 v72, v76, v202
	v_cmp_neq_f32_e32 vcc, 1.0, v154
	s_cbranch_vccz .Lresc_skip_0
	v_pk_mul_f32 v[62:63], v[62:63], v[154:155] op_sel_hi:[1,0]
	v_pk_mul_f32 v[60:61], v[60:61], v[154:155] op_sel_hi:[1,0]
	v_pk_mul_f32 v[58:59], v[58:59], v[154:155] op_sel_hi:[1,0]
	v_pk_mul_f32 v[56:57], v[56:57], v[154:155] op_sel_hi:[1,0]
	v_pk_mul_f32 v[54:55], v[54:55], v[154:155] op_sel_hi:[1,0]
	v_pk_mul_f32 v[52:53], v[52:53], v[154:155] op_sel_hi:[1,0]
	v_pk_mul_f32 v[50:51], v[50:51], v[154:155] op_sel_hi:[1,0]
	v_pk_mul_f32 v[48:49], v[48:49], v[154:155] op_sel_hi:[1,0]
	v_pk_mul_f32 v[46:47], v[46:47], v[154:155] op_sel_hi:[1,0]
	v_pk_mul_f32 v[44:45], v[44:45], v[154:155] op_sel_hi:[1,0]
	v_pk_mul_f32 v[42:43], v[42:43], v[154:155] op_sel_hi:[1,0]
	v_pk_mul_f32 v[40:41], v[40:41], v[154:155] op_sel_hi:[1,0]
	v_pk_mul_f32 v[38:39], v[38:39], v[154:155] op_sel_hi:[1,0]
	v_pk_mul_f32 v[36:37], v[36:37], v[154:155] op_sel_hi:[1,0]
	v_pk_mul_f32 v[34:35], v[34:35], v[154:155] op_sel_hi:[1,0]
	v_pk_mul_f32 v[32:33], v[32:33], v[154:155] op_sel_hi:[1,0]
.Lresc_skip_0:
	v_cvt_pk_bf16_f32 v64, v64, v65
	v_cvt_pk_bf16_f32 v65, v66, v67
	v_cvt_pk_bf16_f32 v66, v68, v69
	v_cvt_pk_bf16_f32 v67, v70, v71
	v_exp_f32_e32 v189, v72
	v_sub_f32_e32 v72, v77, v202
	v_mfma_f32_32x32x16_bf16 v[48:63], v[146:149], v[64:67], v[48:63]
	v_exp_f32_e32 v187, v72
	v_sub_f32_e32 v72, v78, v202
	v_exp_f32_e32 v185, v72
	v_sub_f32_e32 v72, v79, v202
	v_exp_f32_e32 v183, v72
	v_add_f32_e32 v134, v68, v134
	v_add_f32_e32 v134, v69, v134
	v_mfma_f32_32x32x16_bf16 v[32:47], v[204:207], v[64:67], v[32:47]
	v_add_f32_e32 v134, v70, v134
	v_add_f32_e32 v195, v71, v134
	v_cvt_pk_bf16_f32 v68, v199, v197
	v_cvt_pk_bf16_f32 v69, v193, v191
	v_cvt_pk_bf16_f32 v70, v189, v187
	v_cvt_pk_bf16_f32 v71, v185, v183
	s_nop 1
	v_mfma_f32_32x32x16_bf16 v[48:63], v[208:211], v[68:71], v[48:63]
	v_mfma_f32_32x32x16_bf16 v[32:47], v[212:215], v[68:71], v[32:47]
	v_mfma_f32_32x32x16_bf16 v[64:79], v[126:129], v[96:99], 0
	v_mfma_f32_32x32x16_bf16 v[64:79], v[130:133], v[100:103], v[64:79]
	v_mfma_f32_32x32x16_bf16 v[64:79], v[138:141], v[104:107], v[64:79]
	v_mfma_f32_32x32x16_bf16 v[64:79], v[142:145], v[108:111], v[64:79]
	s_nop 11
	v_max_f32_e32 v125, v65, v65
	v_max_f32_e32 v126, v64, v64
	v_max_f32_e32 v125, v126, v125
	v_max3_f32 v125, v125, v66, v67
	v_max3_f32 v125, v125, v68, v69
	v_max3_f32 v125, v125, v70, v71
	v_max3_f32 v125, v125, v72, v73
	v_max3_f32 v125, v125, v74, v75
	v_max3_f32 v125, v125, v76, v77
	v_max3_f32 v125, v125, v78, v79
	ds_bpermute_b32 v126, v248, v125
	s_waitcnt lgkmcnt(0)
	v_max3_f32 v201, v136, v125, v126
	v_sub_f32_e32 v64, v64, v201
	v_exp_f32_e32 v64, v64
	v_sub_f32_e32 v65, v65, v201
	v_exp_f32_e32 v65, v65
	v_sub_f32_e32 v66, v66, v201
	v_sub_f32_e32 v125, v136, v201
	v_exp_f32_e32 v66, v66
	v_sub_f32_e32 v67, v67, v201
	v_sub_f32_e32 v68, v68, v201
	v_sub_f32_e32 v69, v69, v201
	v_sub_f32_e32 v70, v70, v201
	v_sub_f32_e32 v71, v71, v201
	v_exp_f32_e32 v67, v67
	v_exp_f32_e32 v68, v68
	v_exp_f32_e32 v69, v69
	v_exp_f32_e32 v70, v70
	v_exp_f32_e32 v71, v71
	v_sub_f32_e32 v72, v72, v201
	v_exp_f32_e32 v200, v125
	v_add_f32_e32 v126, 0, v64
	v_exp_f32_e32 v198, v72
	v_sub_f32_e32 v72, v73, v201
	v_add_f32_e32 v126, v65, v126
	v_exp_f32_e32 v196, v72
	v_sub_f32_e32 v72, v74, v201
	v_add_f32_e32 v126, v66, v126
	v_exp_f32_e32 v192, v72
	v_sub_f32_e32 v72, v75, v201
	v_add_f32_e32 v126, v67, v126
	v_exp_f32_e32 v190, v72
	v_sub_f32_e32 v72, v76, v201
	v_cmp_neq_f32_e32 vcc, 1.0, v200
	s_cbranch_vccz .Lresc_skip_1
	v_pk_mul_f32 v[30:31], v[30:31], v[200:201] op_sel_hi:[1,0]
	v_pk_mul_f32 v[28:29], v[28:29], v[200:201] op_sel_hi:[1,0]
	v_pk_mul_f32 v[26:27], v[26:27], v[200:201] op_sel_hi:[1,0]
	v_pk_mul_f32 v[24:25], v[24:25], v[200:201] op_sel_hi:[1,0]
	v_pk_mul_f32 v[22:23], v[22:23], v[200:201] op_sel_hi:[1,0]
	v_pk_mul_f32 v[20:21], v[20:21], v[200:201] op_sel_hi:[1,0]
	v_pk_mul_f32 v[18:19], v[18:19], v[200:201] op_sel_hi:[1,0]
	v_pk_mul_f32 v[16:17], v[16:17], v[200:201] op_sel_hi:[1,0]
	v_pk_mul_f32 v[14:15], v[14:15], v[200:201] op_sel_hi:[1,0]
	v_pk_mul_f32 v[12:13], v[12:13], v[200:201] op_sel_hi:[1,0]
	v_pk_mul_f32 v[10:11], v[10:11], v[200:201] op_sel_hi:[1,0]
	v_pk_mul_f32 v[8:9], v[8:9], v[200:201] op_sel_hi:[1,0]
	v_pk_mul_f32 v[6:7], v[6:7], v[200:201] op_sel_hi:[1,0]
	v_pk_mul_f32 v[4:5], v[4:5], v[200:201] op_sel_hi:[1,0]
	v_pk_mul_f32 v[2:3], v[2:3], v[200:201] op_sel_hi:[1,0]
	v_pk_mul_f32 v[0:1], v[0:1], v[200:201] op_sel_hi:[1,0]
; __device__ __forceinline__ unsigned pk2n(float lo, float hi) { const f32x2v v = {lo, hi}; const bf16v2 b = __builtin_convertvector(v, bf16v2); return __builtin_bit_cast(unsigned, b); }
; __device__ __forceinline__ float fexp2(float x) { return __builtin_amdgcn_exp2f(x); }
; template <bool KLDS>
; __device__ __forceinline__ void attn_step(const bf16x8 (&kf)[4], LAS const unsigned char* kb, const bf16x8 (&vf)[2][2], const bf16x8 (&qf)[4], f32x16& o0, f32x16& o1, float& m, float& l, int lane, int maskmode) {
;     ...
;     float tm = S[0];
; #pragma unroll
;     for (int i = 1; i < 16; ++i) tm = fmaxf(tm, S[i]);
;     tm = fmaxf(tm, __shfl_xor(tm, 32));
;     const float mn = fmaxf(m, tm), al = fexp2(m - mn); m = mn;
;     float ps = 0.f;
; #pragma unroll
;     for (int i = 0; i < 16; ++i) { S[i] = fexp2(S[i] - mn); ps += S[i]; }
;     l = l * al + ps;
; #pragma unroll
;     for (int i = 0; i < 16; ++i) { o0[i] *= al; o1[i] *= al; }
;     bf16x8 pf[2];
; #pragma unroll
;     for (int s2 = 0; s2 < 2; ++s2) {
;         u32x4 w; w.x = pk2n(S[8 * s2 + 0], S[8 * s2 + 1]); w.y = pk2n(S[8 * s2 + 2], S[8 * s2 + 3]); w.z = pk2n(S[8 * s2 + 4], S[8 * s2 + 5]); w.w = pk2n(S[8 * s2 + 6], S[8 * s2 + 7]);
;         pf[s2] = __builtin_bit_cast(bf16x8, w);
;     }
; #pragma unroll
;     for (int s2 = 0; s2 < 2; ++s2) {
;         o0 = __builtin_amdgcn_mfma_f32_32x32x16_bf16(vf[s2][0], pf[s2], o0, 0, 0, 0);
;         o1 = __builtin_amdgcn_mfma_f32_32x32x16_bf16(vf[s2][1], pf[s2], o1, 0, 0, 0);
;     }
; __device__ __forceinline__ void attnC_unit(const Args& a, int unit, LAS unsigned char* lds) {
;     ...
;             bf16x8 kf[4], vf[2][2];
;             load_kf(cur + j * 4096, kf, lane); load_vf(cur + 8192 + j * 4096, vf, lane);
; #pragma unroll
;             for (int e = 0; e < 2; ++e) attn_step<false>(kf, cur, vf, qf[e], o0[e], o1[e], m[e], l[e], lane, 0);
.Lresc_skip_1:
	v_cvt_pk_bf16_f32 v64, v64, v65
	v_cvt_pk_bf16_f32 v65, v66, v67
	v_cvt_pk_bf16_f32 v66, v68, v69
	v_cvt_pk_bf16_f32 v67, v70, v71
	v_exp_f32_e32 v188, v72
	v_sub_f32_e32 v72, v77, v201
	v_mfma_f32_32x32x16_bf16 v[16:31], v[146:149], v[64:67], v[16:31]
	v_exp_f32_e32 v186, v72
	v_sub_f32_e32 v72, v78, v201
	v_exp_f32_e32 v184, v72
	v_sub_f32_e32 v72, v79, v201
	v_exp_f32_e32 v182, v72
	v_add_f32_e32 v126, v68, v126
	v_add_f32_e32 v126, v69, v126
	v_mfma_f32_32x32x16_bf16 v[0:15], v[204:207], v[64:67], v[0:15]
	v_add_f32_e32 v126, v70, v126
	v_add_f32_e32 v194, v71, v126
	v_cvt_pk_bf16_f32 v68, v198, v196
	v_cvt_pk_bf16_f32 v69, v192, v190
	v_cvt_pk_bf16_f32 v70, v188, v186
	v_cvt_pk_bf16_f32 v71, v184, v182
	ds_read_b128 v[148:151], v124 offset:4096
	ds_read_b128 v[144:147], v123 offset:4096
	ds_read_b128 v[140:143], v121 offset:4096
	ds_read_b128 v[136:139], v120 offset:4096
	ds_read_b64_tr_b16 v[132:133], v122 offset:12288
	ds_read_b64_tr_b16 v[134:135], v122 offset:13312
	ds_read_b64_tr_b16 v[128:129], v122 offset:12352
	ds_read_b64_tr_b16 v[130:131], v122 offset:13376
	ds_read_b64_tr_b16 v[124:125], v122 offset:14336
	ds_read_b64_tr_b16 v[126:127], v122 offset:15360
	ds_read_b64_tr_b16 v[120:121], v122 offset:14400
	ds_read_b64_tr_b16 v[122:123], v122 offset:15424
	v_mfma_f32_32x32x16_bf16 v[16:31], v[208:211], v[68:71], v[16:31]
	s_waitcnt lgkmcnt(0)
	s_barrier
	v_mfma_f32_32x32x16_bf16 v[0:15], v[212:215], v[68:71], v[0:15]
	v_mfma_f32_32x32x16_bf16 v[64:79], v[148:151], v[80:83], 0
	v_mfma_f32_32x32x16_bf16 v[64:79], v[144:147], v[84:87], v[64:79]
	v_mfma_f32_32x32x16_bf16 v[64:79], v[140:143], v[88:91], v[64:79]
	v_mfma_f32_32x32x16_bf16 v[64:79], v[136:139], v[92:95], v[64:79]
	s_nop 11
	v_max_f32_e32 v152, v65, v65
	v_max_f32_e32 v153, v64, v64
	v_max_f32_e32 v152, v153, v152
	v_max3_f32 v152, v152, v66, v67
	v_max3_f32 v152, v152, v68, v69
	v_max3_f32 v152, v152, v70, v71
	v_max3_f32 v152, v152, v72, v73
	v_max3_f32 v152, v152, v74, v75
	v_max3_f32 v152, v152, v76, v77
	v_max3_f32 v152, v152, v78, v79
	ds_bpermute_b32 v153, v248, v152
	s_waitcnt lgkmcnt(0)
	v_max3_f32 v235, v202, v152, v153
	v_sub_f32_e32 v64, v64, v235
	v_exp_f32_e32 v64, v64
	v_sub_f32_e32 v65, v65, v235
	v_exp_f32_e32 v65, v65
	v_sub_f32_e32 v66, v66, v235
	v_sub_f32_e32 v70, v70, v235
	v_sub_f32_e32 v152, v202, v235
	v_exp_f32_e32 v66, v66
	v_sub_f32_e32 v67, v67, v235
	v_sub_f32_e32 v68, v68, v235
	v_sub_f32_e32 v69, v69, v235
	v_exp_f32_e32 v203, v70
	v_sub_f32_e32 v70, v71, v235
	v_exp_f32_e32 v67, v67
	v_exp_f32_e32 v68, v68
	v_exp_f32_e32 v69, v69
	v_exp_f32_e32 v205, v70
	v_sub_f32_e32 v70, v72, v235
	v_exp_f32_e32 v224, v152
	v_add_f32_e32 v153, 0, v64
	v_exp_f32_e32 v207, v70
	v_sub_f32_e32 v70, v73, v235
	v_add_f32_e32 v153, v65, v153
	v_exp_f32_e32 v209, v70
	v_sub_f32_e32 v70, v74, v235
	v_add_f32_e32 v153, v66, v153
	v_exp_f32_e32 v211, v70
	v_sub_f32_e32 v70, v75, v235
	v_add_f32_e32 v153, v67, v153
	v_exp_f32_e32 v213, v70
	v_sub_f32_e32 v70, v76, v235
	v_cmp_neq_f32_e32 vcc, 1.0, v224
	s_cbranch_vccz .Lresc_skip_2
	v_pk_mul_f32 v[62:63], v[62:63], v[224:225] op_sel_hi:[1,0]
	v_pk_mul_f32 v[60:61], v[60:61], v[224:225] op_sel_hi:[1,0]
	v_pk_mul_f32 v[58:59], v[58:59], v[224:225] op_sel_hi:[1,0]
	v_pk_mul_f32 v[56:57], v[56:57], v[224:225] op_sel_hi:[1,0]
	v_pk_mul_f32 v[54:55], v[54:55], v[224:225] op_sel_hi:[1,0]
	v_pk_mul_f32 v[52:53], v[52:53], v[224:225] op_sel_hi:[1,0]
	v_pk_mul_f32 v[50:51], v[50:51], v[224:225] op_sel_hi:[1,0]
	v_pk_mul_f32 v[48:49], v[48:49], v[224:225] op_sel_hi:[1,0]
	v_pk_mul_f32 v[46:47], v[46:47], v[224:225] op_sel_hi:[1,0]
	v_pk_mul_f32 v[44:45], v[44:45], v[224:225] op_sel_hi:[1,0]
	v_pk_mul_f32 v[42:43], v[42:43], v[224:225] op_sel_hi:[1,0]
	v_pk_mul_f32 v[40:41], v[40:41], v[224:225] op_sel_hi:[1,0]
	v_pk_mul_f32 v[38:39], v[38:39], v[224:225] op_sel_hi:[1,0]
	v_pk_mul_f32 v[36:37], v[36:37], v[224:225] op_sel_hi:[1,0]
	v_pk_mul_f32 v[34:35], v[34:35], v[224:225] op_sel_hi:[1,0]
	v_pk_mul_f32 v[32:33], v[32:33], v[224:225] op_sel_hi:[1,0]
; __device__ __forceinline__ unsigned pk2n(float lo, float hi) { const f32x2v v = {lo, hi}; const bf16v2 b = __builtin_convertvector(v, bf16v2); return __builtin_bit_cast(unsigned, b); }
; __device__ __forceinline__ float fexp2(float x) { return __builtin_amdgcn_exp2f(x); }
; template <bool KLDS>
; __device__ __forceinline__ void attn_step(const bf16x8 (&kf)[4], LAS const unsigned char* kb, const bf16x8 (&vf)[2][2], const bf16x8 (&qf)[4], f32x16& o0, f32x16& o1, float& m, float& l, int lane, int maskmode) {
;     ...
;     float tm = S[0];
; #pragma unroll
;     for (int i = 1; i < 16; ++i) tm = fmaxf(tm, S[i]);
;     tm = fmaxf(tm, __shfl_xor(tm, 32));
;     const float mn = fmaxf(m, tm), al = fexp2(m - mn); m = mn;
;     float ps = 0.f;
; #pragma unroll
;     for (int i = 0; i < 16; ++i) { S[i] = fexp2(S[i] - mn); ps += S[i]; }
;     l = l * al + ps;
; #pragma unroll
;     for (int i = 0; i < 16; ++i) { o0[i] *= al; o1[i] *= al; }
;     bf16x8 pf[2];
; #pragma unroll
;     for (int s2 = 0; s2 < 2; ++s2) {
;         u32x4 w; w.x = pk2n(S[8 * s2 + 0], S[8 * s2 + 1]); w.y = pk2n(S[8 * s2 + 2], S[8 * s2 + 3]); w.z = pk2n(S[8 * s2 + 4], S[8 * s2 + 5]); w.w = pk2n(S[8 * s2 + 6], S[8 * s2 + 7]);
;         pf[s2] = __builtin_bit_cast(bf16x8, w);
;     }
; #pragma unroll
;     for (int s2 = 0; s2 < 2; ++s2) {
;         o0 = __builtin_amdgcn_mfma_f32_32x32x16_bf16(vf[s2][0], pf[s2], o0, 0, 0, 0);
;         o1 = __builtin_amdgcn_mfma_f32_32x32x16_bf16(vf[s2][1], pf[s2], o1, 0, 0, 0);
;     }
; __device__ __forceinline__ void attnC_unit(const Args& a, int unit, LAS unsigned char* lds) {
;     ...
;             bf16x8 kf[4], vf[2][2];
;             load_kf(cur + j * 4096, kf, lane); load_vf(cur + 8192 + j * 4096, vf, lane);
; #pragma unroll
;             for (int e = 0; e < 2; ++e) attn_step<false>(kf, cur, vf, qf[e], o0[e], o1[e], m[e], l[e], lane, 0);
.Lresc_skip_2:
	v_cvt_pk_bf16_f32 v64, v64, v65
	v_cvt_pk_bf16_f32 v65, v66, v67
	v_cvt_pk_bf16_f32 v66, v68, v69
	v_cvt_pk_bf16_f32 v67, v203, v205
	v_exp_f32_e32 v215, v70
	v_sub_f32_e32 v70, v77, v235
	v_mfma_f32_32x32x16_bf16 v[48:63], v[132:135], v[64:67], v[48:63]
	v_exp_f32_e32 v217, v70
	v_sub_f32_e32 v70, v78, v235
	v_exp_f32_e32 v219, v70
	v_sub_f32_e32 v70, v79, v235
	v_exp_f32_e32 v221, v70
	v_add_f32_e32 v153, v68, v153
	v_add_f32_e32 v223, v69, v153
	v_mfma_f32_32x32x16_bf16 v[32:47], v[128:131], v[64:67], v[32:47]
	v_cvt_pk_bf16_f32 v68, v207, v209
	v_cvt_pk_bf16_f32 v69, v211, v213
	v_cvt_pk_bf16_f32 v70, v215, v217
	v_cvt_pk_bf16_f32 v71, v219, v221
	s_nop 1
	v_mfma_f32_32x32x16_bf16 v[48:63], v[124:127], v[68:71], v[48:63]
	v_mfma_f32_32x32x16_bf16 v[32:47], v[120:123], v[68:71], v[32:47]
	v_mfma_f32_32x32x16_bf16 v[64:79], v[148:151], v[96:99], 0
	v_mfma_f32_32x32x16_bf16 v[64:79], v[144:147], v[100:103], v[64:79]
	v_mfma_f32_32x32x16_bf16 v[64:79], v[140:143], v[104:107], v[64:79]
	v_mfma_f32_32x32x16_bf16 v[64:79], v[136:139], v[108:111], v[64:79]
	s_nop 11
	v_max_f32_e32 v136, v65, v65
	v_max_f32_e32 v137, v64, v64
	v_max_f32_e32 v136, v137, v136
	v_max3_f32 v136, v136, v66, v67
	v_max3_f32 v136, v136, v68, v69
	v_max3_f32 v136, v136, v70, v71
	v_max3_f32 v136, v136, v72, v73
	v_max3_f32 v136, v136, v74, v75
	v_max3_f32 v136, v136, v76, v77
	v_max3_f32 v136, v136, v78, v79
	ds_bpermute_b32 v137, v248, v136
	s_waitcnt lgkmcnt(0)
	v_max3_f32 v136, v201, v136, v137
	v_sub_f32_e32 v64, v64, v136
	v_exp_f32_e32 v138, v64
	v_sub_f32_e32 v65, v65, v136
	v_exp_f32_e32 v139, v65
	v_sub_f32_e32 v65, v66, v136
	v_exp_f32_e32 v140, v65
	v_sub_f32_e32 v65, v67, v136
	v_exp_f32_e32 v141, v65
	v_sub_f32_e32 v65, v68, v136
	v_add_f32_e32 v64, 0, v138
	v_exp_f32_e32 v142, v65
	v_sub_f32_e32 v65, v69, v136
	v_add_f32_e32 v64, v139, v64
	v_exp_f32_e32 v143, v65
	v_add_f32_e32 v64, v140, v64
	v_add_f32_e32 v64, v141, v64
	v_add_f32_e32 v64, v142, v64
	v_add_f32_e32 v222, v143, v64
	v_sub_f32_e32 v64, v70, v136
	v_exp_f32_e32 v202, v64
	v_sub_f32_e32 v64, v71, v136
	v_exp_f32_e32 v204, v64
	v_sub_f32_e32 v64, v72, v136
	v_exp_f32_e32 v206, v64
	v_sub_f32_e32 v64, v73, v136
	v_exp_f32_e32 v208, v64
	v_sub_f32_e32 v64, v74, v136
	v_exp_f32_e32 v210, v64
	v_sub_f32_e32 v64, v75, v136
	v_pk_add_f32 v[68:69], v[202:203], v[222:223]
	v_exp_f32_e32 v212, v64
	v_sub_f32_e32 v64, v76, v136
	v_pk_add_f32 v[66:67], v[198:199], v[194:195]
	v_pk_add_f32 v[68:69], v[204:205], v[68:69]
	v_exp_f32_e32 v214, v64
	v_sub_f32_e32 v64, v77, v136
	v_pk_add_f32 v[66:67], v[196:197], v[66:67]
	v_pk_add_f32 v[68:69], v[206:207], v[68:69]
	v_exp_f32_e32 v216, v64
	v_sub_f32_e32 v64, v78, v136
	v_pk_add_f32 v[66:67], v[192:193], v[66:67]
	v_pk_add_f32 v[68:69], v[208:209], v[68:69]
	v_exp_f32_e32 v218, v64
	v_sub_f32_e32 v64, v79, v136
	v_pk_add_f32 v[66:67], v[190:191], v[66:67]
	v_pk_add_f32 v[68:69], v[210:211], v[68:69]
	v_sub_f32_e32 v137, v201, v136
	v_exp_f32_e32 v220, v64
	v_pk_add_f32 v[66:67], v[188:189], v[66:67]
	v_pk_add_f32 v[68:69], v[212:213], v[68:69]
	v_exp_f32_e32 v64, v137
	v_pk_add_f32 v[66:67], v[186:187], v[66:67]
	v_pk_add_f32 v[68:69], v[214:215], v[68:69]
	v_pk_add_f32 v[66:67], v[184:185], v[66:67]
	v_pk_add_f32 v[68:69], v[216:217], v[68:69]
	v_pk_add_f32 v[66:67], v[182:183], v[66:67]
	v_mov_b32_e32 v201, v154
	v_pk_add_f32 v[68:69], v[218:219], v[68:69]
	v_pk_fma_f32 v[66:67], v[178:179], v[200:201], v[66:67]
	v_pk_add_f32 v[68:69], v[220:221], v[68:69]
	v_mov_b32_e32 v65, v224
	v_pk_fma_f32 v[178:179], v[66:67], v[64:65], v[68:69]
	v_cmp_neq_f32_e32 vcc, 1.0, v64
	s_cbranch_vccz .Lresc_skip_3
	v_pk_mul_f32 v[30:31], v[30:31], v[64:65] op_sel_hi:[1,0]
	v_pk_mul_f32 v[28:29], v[28:29], v[64:65] op_sel_hi:[1,0]
	v_pk_mul_f32 v[26:27], v[26:27], v[64:65] op_sel_hi:[1,0]
	v_pk_mul_f32 v[24:25], v[24:25], v[64:65] op_sel_hi:[1,0]
	v_pk_mul_f32 v[22:23], v[22:23], v[64:65] op_sel_hi:[1,0]
	v_pk_mul_f32 v[20:21], v[20:21], v[64:65] op_sel_hi:[1,0]
	v_pk_mul_f32 v[18:19], v[18:19], v[64:65] op_sel_hi:[1,0]
	v_pk_mul_f32 v[16:17], v[16:17], v[64:65] op_sel_hi:[1,0]
	v_pk_mul_f32 v[14:15], v[14:15], v[64:65] op_sel_hi:[1,0]
	v_pk_mul_f32 v[12:13], v[12:13], v[64:65] op_sel_hi:[1,0]
	v_pk_mul_f32 v[10:11], v[10:11], v[64:65] op_sel_hi:[1,0]
	v_pk_mul_f32 v[8:9], v[8:9], v[64:65] op_sel_hi:[1,0]
	v_pk_mul_f32 v[6:7], v[6:7], v[64:65] op_sel_hi:[1,0]
	v_pk_mul_f32 v[4:5], v[4:5], v[64:65] op_sel_hi:[1,0]
	v_pk_mul_f32 v[2:3], v[2:3], v[64:65] op_sel_hi:[1,0]
	v_pk_mul_f32 v[0:1], v[0:1], v[64:65] op_sel_hi:[1,0]
.Lresc_skip_3:
	v_cvt_pk_bf16_f32 v64, v138, v139
	v_cvt_pk_bf16_f32 v65, v140, v141
	v_cvt_pk_bf16_f32 v66, v142, v143
	v_cvt_pk_bf16_f32 v67, v202, v204
	v_cvt_pk_bf16_f32 v68, v206, v208
	v_cvt_pk_bf16_f32 v69, v210, v212
	v_mfma_f32_32x32x16_bf16 v[16:31], v[132:135], v[64:67], v[16:31]
	v_cvt_pk_bf16_f32 v70, v214, v216
	v_cvt_pk_bf16_f32 v71, v218, v220
	v_mfma_f32_32x32x16_bf16 v[0:15], v[128:131], v[64:67], v[0:15]
	s_nop 0
	v_mfma_f32_32x32x16_bf16 v[16:31], v[124:127], v[68:71], v[16:31]
	v_mfma_f32_32x32x16_bf16 v[0:15], v[120:123], v[68:71], v[0:15]
	s_cbranch_scc0 .LBB0_252

; __device__ __forceinline__ unsigned pk2(float lo, float hi) { unsigned r; asm("v_cvt_pk_bf16_f32 %0, %1, %2" : "=v"(r) : "v"(lo), "v"(hi)); return r; }
;     __device__ __forceinline__ void operator()(const f32x4 (&acc)[2][2][4][2], const Unit& uu, int wr, int wc, int fr, int fq) const {
;     ...
;         if (ch < 12) {
;             const float qs = (ch < 6) ? 0.125f * LOG2E : 1.0f;
; #pragma unroll
;             for (int ai = 0; ai < 2; ++ai)
; #pragma unroll
;                 for (int m = 0; m < 4; ++m) {
;                     const int r = rowb + 128 * ai + 16 * m, s = r & 2047;
;                     u32x4 w1, w2;
;                     {
;                         const f32x4 c0 = *(const f32x4*)(rac + s * 32 + 8 * fq), s0 = *(const f32x4*)(ras + s * 32 + 8 * fq);
;                         const f32x4 c1 = *(const f32x4*)(rac + s * 32 + 8 * fq + 4), s1 = *(const f32x4*)(ras + s * 32 + 8 * fq + 4);
;                         const f32x4 x10 = acc[ai][0][m][0], x11 = acc[ai][0][m][1], x20 = acc[ai][1][m][0], x21 = acc[ai][1][m][1];
;                         const f32x4 a0 = (x10 * c0 - x20 * s0) * qs, a1 = (x11 * c1 - x21 * s1) * qs;
;                         const f32x4 b0 = (x20 * c0 + x10 * s0) * qs, b1 = (x21 * c1 + x11 * s1) * qs;
;                         w1.x = pk2(a0[0], a0[1]); w1.y = pk2(a0[2], a0[3]); w1.z = pk2(a1[0], a1[1]); w1.w = pk2(a1[2], a1[3]);
;                         w2.x = pk2(b0[0], b0[1]); w2.y = pk2(b0[2], b0[3]); w2.z = pk2(b1[0], b1[1]); w2.w = pk2(b1[2], b1[3]);
;                     }
;                     bf16_t* dst = P + (size_t)r * PW + 64 * ch + 8 * fq;
;                     *(u32x4*)dst = w1; *(u32x4*)(dst + 32) = w2;
;                 }
.LBB0_330:
	s_andn2_b64 vcc, exec, s[24:25]
	s_cbranch_vccnz .LBB0_315
	v_lshlrev_b32_e32 v132, 3, v210
	v_lshlrev_b32_e32 v129, 7, v209
	v_ashrrev_i32_e32 v133, 31, v132
	v_and_b32_e32 v154, 0x3ff80, v129
	v_lshl_add_u64 v[134:135], s[6:7], 0, v[154:155]
	v_lshlrev_b64 v[130:131], 2, v[132:133]
	v_lshl_add_u64 v[142:143], s[8:9], 0, v[154:155]
	v_lshl_add_u64 v[138:139], v[134:135], 0, v[130:131]
	v_lshl_add_u64 v[146:147], v[142:143], 0, v[130:131]
	global_load_dwordx4 v[134:137], v[138:139], off offset:16
	s_nop 0
	global_load_dwordx4 v[138:141], v[138:139], off
	s_nop 0
	global_load_dwordx4 v[142:145], v[146:147], off offset:16
	s_nop 0
	global_load_dwordx4 v[146:149], v[146:147], off
	s_cmp_lt_i32 s17, 6
	s_cselect_b64 vcc, -1, 0
	v_cndmask_b32_e32 v128, 1.0, v252, vcc
	s_lshl_b32 s2, s17, 6
	s_ashr_i32 s3, s2, 31
	s_movk_i32 s17, 0x1400
	s_lshl_b64 s[2:3], s[2:3], 1
	s_waitcnt vmcnt(0)
	v_add_u32_e32 v175, 0x10, v209
	v_lshlrev_b32_e32 v175, 7, v175
	v_and_b32_e32 v175, 0x3ff80, v175
	v_add_u32_e32 v175, v130, v175
	global_load_dwordx4 v[158:161], v175, s[6:7] offset:16
	global_load_dwordx4 v[162:165], v175, s[6:7]
	global_load_dwordx4 v[166:169], v175, s[8:9] offset:16
	global_load_dwordx4 v[170:173], v175, s[8:9]
	v_pk_mul_f32 v[186:187], v[112:113], v[142:143]
	v_pk_mul_f32 v[150:151], v[118:119], v[148:149]
	v_pk_mul_f32 v[156:157], v[116:117], v[146:147]
	v_pk_fma_f32 v[150:151], v[126:127], v[140:141], v[150:151] neg_lo:[0,0,1] neg_hi:[0,0,1]
	v_pk_mul_f32 v[126:127], v[126:127], v[148:149]
	v_pk_fma_f32 v[156:157], v[124:125], v[138:139], v[156:157] neg_lo:[0,0,1] neg_hi:[0,0,1]
	v_pk_mul_f32 v[124:125], v[124:125], v[146:147]
	v_pk_fma_f32 v[118:119], v[118:119], v[140:141], v[126:127]
	v_pk_fma_f32 v[116:117], v[116:117], v[138:139], v[124:125]
	v_pk_mul_f32 v[124:125], v[128:129], v[118:119] op_sel_hi:[0,1]
	v_pk_mul_f32 v[118:119], v[120:121], v[142:143]
	v_pk_mul_f32 v[126:127], v[128:129], v[116:117] op_sel_hi:[0,1]
	v_pk_mul_f32 v[116:117], v[122:123], v[144:145]
	v_pk_fma_f32 v[112:113], v[112:113], v[134:135], v[118:119]
	v_pk_mul_f32 v[184:185], v[114:115], v[144:145]
	v_pk_fma_f32 v[114:115], v[114:115], v[136:137], v[116:117]
	v_pk_mul_f32 v[112:113], v[128:129], v[112:113] op_sel_hi:[0,1]
	v_pk_fma_f32 v[184:185], v[122:123], v[136:137], v[184:185] neg_lo:[0,0,1] neg_hi:[0,0,1]
	v_pk_mul_f32 v[114:115], v[128:129], v[114:115] op_sel_hi:[0,1]
	v_cvt_pk_bf16_f32 v122, v112, v113
	v_mov_b64_e32 v[112:113], s[0:1]
	v_cvt_pk_bf16_f32 v123, v114, v115
	v_mad_i64_i32 v[114:115], s[24:25], v209, s17, v[112:113]
	v_pk_fma_f32 v[186:187], v[120:121], v[134:135], v[186:187] neg_lo:[0,0,1] neg_hi:[0,0,1]
	v_cvt_pk_bf16_f32 v121, v124, v125
	v_lshl_add_u64 v[124:125], v[114:115], 0, s[2:3]
	v_lshlrev_b64 v[114:115], 1, v[132:133]
	v_pk_mul_f32 v[150:151], v[128:129], v[150:151] op_sel_hi:[0,1]
	v_pk_mul_f32 v[156:157], v[128:129], v[156:157] op_sel_hi:[0,1]
	v_pk_mul_f32 v[184:185], v[128:129], v[184:185] op_sel_hi:[0,1]
	v_pk_mul_f32 v[186:187], v[128:129], v[186:187] op_sel_hi:[0,1]
	v_cvt_pk_bf16_f32 v116, v156, v157
	v_cvt_pk_bf16_f32 v117, v150, v151
	v_cvt_pk_bf16_f32 v118, v186, v187
	v_cvt_pk_bf16_f32 v119, v184, v185
	v_lshl_add_u64 v[124:125], v[124:125], 0, v[114:115]
	v_add_u32_e32 v129, 16, v209
	v_cvt_pk_bf16_f32 v120, v126, v127
	global_store_dwordx4 v[124:125], v[116:119], off
	global_store_dwordx4 v[124:125], v[120:123], off offset:64
	s_nop 0
	v_lshlrev_b32_e32 v116, 7, v129
	v_and_b32_e32 v154, 0x3ff80, v116
	v_lshl_add_u64 v[116:117], s[6:7], 0, v[154:155]
	v_lshl_add_u64 v[124:125], s[8:9], 0, v[154:155]
	v_lshl_add_u64 v[120:121], v[116:117], 0, v[130:131]
	v_lshl_add_u64 v[132:133], v[124:125], 0, v[130:131]
	s_waitcnt vmcnt(2)
	v_mov_b32_e32 v116, v158
	v_mov_b32_e32 v117, v159
	v_mov_b32_e32 v118, v160
	v_mov_b32_e32 v119, v161
	v_mov_b32_e32 v120, v162
	v_mov_b32_e32 v121, v163
	v_mov_b32_e32 v122, v164
	v_mov_b32_e32 v123, v165
	v_mov_b32_e32 v124, v166
	v_mov_b32_e32 v125, v167
	v_mov_b32_e32 v126, v168
	v_mov_b32_e32 v127, v169
	v_mov_b32_e32 v132, v170
	v_mov_b32_e32 v133, v171
	v_mov_b32_e32 v134, v172
	v_mov_b32_e32 v135, v173
	v_add_u32_e32 v175, 0x20, v209
	v_lshlrev_b32_e32 v175, 7, v175
	v_and_b32_e32 v175, 0x3ff80, v175
	v_add_u32_e32 v175, v130, v175
	global_load_dwordx4 v[158:161], v175, s[6:7] offset:16
	global_load_dwordx4 v[162:165], v175, s[6:7]
	global_load_dwordx4 v[166:169], v175, s[8:9] offset:16
	global_load_dwordx4 v[170:173], v175, s[8:9]
	v_pk_mul_f32 v[140:141], v[98:99], v[126:127]
	v_pk_mul_f32 v[136:137], v[102:103], v[134:135]
	v_pk_mul_f32 v[138:139], v[100:101], v[132:133]
	v_pk_fma_f32 v[136:137], v[110:111], v[122:123], v[136:137] neg_lo:[0,0,1] neg_hi:[0,0,1]
	v_pk_fma_f32 v[138:139], v[108:109], v[120:121], v[138:139] neg_lo:[0,0,1] neg_hi:[0,0,1]
	v_pk_mul_f32 v[142:143], v[96:97], v[124:125]
	v_pk_fma_f32 v[140:141], v[106:107], v[118:119], v[140:141] neg_lo:[0,0,1] neg_hi:[0,0,1]
	v_pk_mul_f32 v[110:111], v[110:111], v[134:135]
	v_pk_mul_f32 v[108:109], v[108:109], v[132:133]
	v_pk_mul_f32 v[106:107], v[106:107], v[126:127]
	v_pk_fma_f32 v[142:143], v[104:105], v[116:117], v[142:143] neg_lo:[0,0,1] neg_hi:[0,0,1]
	v_pk_fma_f32 v[102:103], v[102:103], v[122:123], v[110:111]
	v_pk_fma_f32 v[100:101], v[100:101], v[120:121], v[108:109]
	v_pk_mul_f32 v[104:105], v[104:105], v[124:125]
	v_pk_fma_f32 v[98:99], v[98:99], v[118:119], v[106:107]
	v_pk_mul_f32 v[102:103], v[128:129], v[102:103] op_sel_hi:[0,1]
	v_pk_mul_f32 v[100:101], v[128:129], v[100:101] op_sel_hi:[0,1]
	v_pk_fma_f32 v[96:97], v[96:97], v[116:117], v[104:105]
	v_pk_mul_f32 v[104:105], v[128:129], v[98:99] op_sel_hi:[0,1]
	v_cvt_pk_bf16_f32 v100, v100, v101
	v_cvt_pk_bf16_f32 v101, v102, v103
	v_cvt_pk_bf16_f32 v103, v104, v105
	v_mad_i64_i32 v[104:105], s[24:25], v129, s17, v[112:113]
	v_lshl_add_u64 v[104:105], v[104:105], 0, s[2:3]
	v_pk_mul_f32 v[136:137], v[128:129], v[136:137] op_sel_hi:[0,1]
	v_pk_mul_f32 v[138:139], v[128:129], v[138:139] op_sel_hi:[0,1]
	v_pk_mul_f32 v[140:141], v[128:129], v[140:141] op_sel_hi:[0,1]
	v_pk_mul_f32 v[142:143], v[128:129], v[142:143] op_sel_hi:[0,1]
	v_pk_mul_f32 v[106:107], v[128:129], v[96:97] op_sel_hi:[0,1]
	v_cvt_pk_bf16_f32 v96, v138, v139
	v_cvt_pk_bf16_f32 v97, v136, v137
	v_cvt_pk_bf16_f32 v98, v142, v143
	v_cvt_pk_bf16_f32 v99, v140, v141
	v_lshl_add_u64 v[104:105], v[104:105], 0, v[114:115]
	v_add_u32_e32 v124, 32, v209
	v_cvt_pk_bf16_f32 v102, v106, v107
	global_store_dwordx4 v[104:105], v[96:99], off
	global_store_dwordx4 v[104:105], v[100:103], off offset:64
	s_nop 0
	v_lshlrev_b32_e32 v96, 7, v124
	v_and_b32_e32 v154, 0x3ff80, v96
	v_lshl_add_u64 v[96:97], s[6:7], 0, v[154:155]
	v_lshl_add_u64 v[104:105], s[8:9], 0, v[154:155]
	v_lshl_add_u64 v[100:101], v[96:97], 0, v[130:131]
	v_lshl_add_u64 v[108:109], v[104:105], 0, v[130:131]
	s_waitcnt vmcnt(2)
; __device__ __forceinline__ unsigned pk2(float lo, float hi) { unsigned r; asm("v_cvt_pk_bf16_f32 %0, %1, %2" : "=v"(r) : "v"(lo), "v"(hi)); return r; }
;     __device__ __forceinline__ void operator()(const f32x4 (&acc)[2][2][4][2], const Unit& uu, int wr, int wc, int fr, int fq) const {
;     ...
;             for (int ai = 0; ai < 2; ++ai)
; #pragma unroll
;                 for (int m = 0; m < 4; ++m) {
;                     const int r = rowb + 128 * ai + 16 * m, s = r & 2047;
;                     u32x4 w1, w2;
;                     {
;                         const f32x4 c0 = *(const f32x4*)(rac + s * 32 + 8 * fq), s0 = *(const f32x4*)(ras + s * 32 + 8 * fq);
;                         const f32x4 c1 = *(const f32x4*)(rac + s * 32 + 8 * fq + 4), s1 = *(const f32x4*)(ras + s * 32 + 8 * fq + 4);
;                         const f32x4 x10 = acc[ai][0][m][0], x11 = acc[ai][0][m][1], x20 = acc[ai][1][m][0], x21 = acc[ai][1][m][1];
;                         const f32x4 a0 = (x10 * c0 - x20 * s0) * qs, a1 = (x11 * c1 - x21 * s1) * qs;
;                         const f32x4 b0 = (x20 * c0 + x10 * s0) * qs, b1 = (x21 * c1 + x11 * s1) * qs;
;                         w1.x = pk2(a0[0], a0[1]); w1.y = pk2(a0[2], a0[3]); w1.z = pk2(a1[0], a1[1]); w1.w = pk2(a1[2], a1[3]);
;                         w2.x = pk2(b0[0], b0[1]); w2.y = pk2(b0[2], b0[3]); w2.z = pk2(b1[0], b1[1]); w2.w = pk2(b1[2], b1[3]);
;                     }
;                     bf16_t* dst = P + (size_t)r * PW + 64 * ch + 8 * fq;
;                     *(u32x4*)dst = w1; *(u32x4*)(dst + 32) = w2;
;                 }
	v_mov_b32_e32 v96, v158
	v_mov_b32_e32 v97, v159
	v_mov_b32_e32 v98, v160
	v_mov_b32_e32 v99, v161
	v_mov_b32_e32 v100, v162
	v_mov_b32_e32 v101, v163
	v_mov_b32_e32 v102, v164
	v_mov_b32_e32 v103, v165
	v_mov_b32_e32 v104, v166
	v_mov_b32_e32 v105, v167
	v_mov_b32_e32 v106, v168
	v_mov_b32_e32 v107, v169
	v_mov_b32_e32 v108, v170
	v_mov_b32_e32 v109, v171
	v_mov_b32_e32 v110, v172
	v_mov_b32_e32 v111, v173
	v_add_u32_e32 v175, 0x30, v209
	v_lshlrev_b32_e32 v175, 7, v175
	v_and_b32_e32 v175, 0x3ff80, v175
	v_add_u32_e32 v175, v130, v175
	global_load_dwordx4 v[158:161], v175, s[6:7] offset:16
	global_load_dwordx4 v[162:165], v175, s[6:7]
	global_load_dwordx4 v[166:169], v175, s[8:9] offset:16
	global_load_dwordx4 v[170:173], v175, s[8:9]
	v_pk_mul_f32 v[120:121], v[82:83], v[106:107]
	v_pk_mul_f32 v[116:117], v[86:87], v[110:111]
	v_pk_mul_f32 v[118:119], v[84:85], v[108:109]
	v_pk_fma_f32 v[116:117], v[94:95], v[102:103], v[116:117] neg_lo:[0,0,1] neg_hi:[0,0,1]
	v_pk_fma_f32 v[118:119], v[92:93], v[100:101], v[118:119] neg_lo:[0,0,1] neg_hi:[0,0,1]
	v_pk_mul_f32 v[122:123], v[80:81], v[104:105]
	v_pk_fma_f32 v[120:121], v[90:91], v[98:99], v[120:121] neg_lo:[0,0,1] neg_hi:[0,0,1]
	v_pk_mul_f32 v[94:95], v[94:95], v[110:111]
	v_pk_mul_f32 v[92:93], v[92:93], v[108:109]
	v_pk_mul_f32 v[90:91], v[90:91], v[106:107]
	v_pk_fma_f32 v[122:123], v[88:89], v[96:97], v[122:123] neg_lo:[0,0,1] neg_hi:[0,0,1]
	v_pk_fma_f32 v[86:87], v[86:87], v[102:103], v[94:95]
	v_pk_fma_f32 v[84:85], v[84:85], v[100:101], v[92:93]
	v_pk_mul_f32 v[88:89], v[88:89], v[104:105]
	v_pk_fma_f32 v[82:83], v[82:83], v[98:99], v[90:91]
	v_pk_mul_f32 v[86:87], v[128:129], v[86:87] op_sel_hi:[0,1]
	v_pk_mul_f32 v[84:85], v[128:129], v[84:85] op_sel_hi:[0,1]
	v_pk_fma_f32 v[80:81], v[80:81], v[96:97], v[88:89]
	v_pk_mul_f32 v[88:89], v[128:129], v[82:83] op_sel_hi:[0,1]
	v_cvt_pk_bf16_f32 v84, v84, v85
	v_cvt_pk_bf16_f32 v85, v86, v87
	v_cvt_pk_bf16_f32 v87, v88, v89
	v_mad_i64_i32 v[88:89], s[24:25], v124, s17, v[112:113]
	v_lshl_add_u64 v[88:89], v[88:89], 0, s[2:3]
	v_pk_mul_f32 v[116:117], v[128:129], v[116:117] op_sel_hi:[0,1]
	v_pk_mul_f32 v[118:119], v[128:129], v[118:119] op_sel_hi:[0,1]
	v_pk_mul_f32 v[120:121], v[128:129], v[120:121] op_sel_hi:[0,1]
	v_pk_mul_f32 v[122:123], v[128:129], v[122:123] op_sel_hi:[0,1]
	v_pk_mul_f32 v[90:91], v[128:129], v[80:81] op_sel_hi:[0,1]
	v_cvt_pk_bf16_f32 v80, v118, v119
	v_cvt_pk_bf16_f32 v81, v116, v117
	v_cvt_pk_bf16_f32 v82, v122, v123
	v_cvt_pk_bf16_f32 v83, v120, v121
	v_lshl_add_u64 v[88:89], v[88:89], 0, v[114:115]
	v_add_u32_e32 v104, 48, v209
	v_cvt_pk_bf16_f32 v86, v90, v91
	global_store_dwordx4 v[88:89], v[80:83], off
	global_store_dwordx4 v[88:89], v[84:87], off offset:64
	s_nop 0
	v_lshlrev_b32_e32 v80, 7, v104
	v_and_b32_e32 v154, 0x3ff80, v80
	v_lshl_add_u64 v[80:81], s[6:7], 0, v[154:155]
	v_lshl_add_u64 v[88:89], s[8:9], 0, v[154:155]
	v_lshl_add_u64 v[84:85], v[80:81], 0, v[130:131]
	v_lshl_add_u64 v[92:93], v[88:89], 0, v[130:131]
	s_waitcnt vmcnt(2)
	v_mov_b32_e32 v80, v158
	v_mov_b32_e32 v81, v159
	v_mov_b32_e32 v82, v160
	v_mov_b32_e32 v83, v161
	v_mov_b32_e32 v84, v162
	v_mov_b32_e32 v85, v163
	v_mov_b32_e32 v86, v164
	v_mov_b32_e32 v87, v165
	v_mov_b32_e32 v88, v166
	v_mov_b32_e32 v89, v167
	v_mov_b32_e32 v90, v168
	v_mov_b32_e32 v91, v169
	v_mov_b32_e32 v92, v170
	v_mov_b32_e32 v93, v171
	v_mov_b32_e32 v94, v172
	v_mov_b32_e32 v95, v173
	v_add_u32_e32 v175, 0x80, v209
	v_lshlrev_b32_e32 v175, 7, v175
	v_and_b32_e32 v175, 0x3ff80, v175
	v_add_u32_e32 v175, v130, v175
	global_load_dwordx4 v[158:161], v175, s[6:7] offset:16
	global_load_dwordx4 v[162:165], v175, s[6:7]
	global_load_dwordx4 v[166:169], v175, s[8:9] offset:16
	global_load_dwordx4 v[170:173], v175, s[8:9]
	v_pk_mul_f32 v[100:101], v[66:67], v[90:91]
	v_pk_mul_f32 v[96:97], v[70:71], v[94:95]
	v_pk_mul_f32 v[98:99], v[68:69], v[92:93]
	v_pk_fma_f32 v[96:97], v[78:79], v[86:87], v[96:97] neg_lo:[0,0,1] neg_hi:[0,0,1]
	v_pk_fma_f32 v[98:99], v[76:77], v[84:85], v[98:99] neg_lo:[0,0,1] neg_hi:[0,0,1]
	v_pk_mul_f32 v[102:103], v[64:65], v[88:89]
	v_pk_fma_f32 v[100:101], v[74:75], v[82:83], v[100:101] neg_lo:[0,0,1] neg_hi:[0,0,1]
	v_pk_mul_f32 v[78:79], v[78:79], v[94:95]
	v_pk_mul_f32 v[76:77], v[76:77], v[92:93]
	v_pk_mul_f32 v[74:75], v[74:75], v[90:91]
	v_pk_fma_f32 v[102:103], v[72:73], v[80:81], v[102:103] neg_lo:[0,0,1] neg_hi:[0,0,1]
	v_pk_fma_f32 v[70:71], v[70:71], v[86:87], v[78:79]
	v_pk_fma_f32 v[68:69], v[68:69], v[84:85], v[76:77]
	v_pk_mul_f32 v[72:73], v[72:73], v[88:89]
	v_pk_fma_f32 v[66:67], v[66:67], v[82:83], v[74:75]
	v_pk_mul_f32 v[70:71], v[128:129], v[70:71] op_sel_hi:[0,1]
	v_pk_mul_f32 v[68:69], v[128:129], v[68:69] op_sel_hi:[0,1]
	v_pk_fma_f32 v[64:65], v[64:65], v[80:81], v[72:73]
	v_pk_mul_f32 v[72:73], v[128:129], v[66:67] op_sel_hi:[0,1]
	v_cvt_pk_bf16_f32 v68, v68, v69
	v_cvt_pk_bf16_f32 v69, v70, v71
	v_cvt_pk_bf16_f32 v71, v72, v73
	v_mad_i64_i32 v[72:73], s[24:25], v104, s17, v[112:113]
	v_lshl_add_u64 v[72:73], v[72:73], 0, s[2:3]
	v_pk_mul_f32 v[96:97], v[128:129], v[96:97] op_sel_hi:[0,1]
	v_pk_mul_f32 v[98:99], v[128:129], v[98:99] op_sel_hi:[0,1]
	v_pk_mul_f32 v[100:101], v[128:129], v[100:101] op_sel_hi:[0,1]
	v_pk_mul_f32 v[102:103], v[128:129], v[102:103] op_sel_hi:[0,1]
	v_pk_mul_f32 v[74:75], v[128:129], v[64:65] op_sel_hi:[0,1]
	v_cvt_pk_bf16_f32 v64, v98, v99
	v_cvt_pk_bf16_f32 v65, v96, v97
	v_cvt_pk_bf16_f32 v66, v102, v103
	v_cvt_pk_bf16_f32 v67, v100, v101
	v_lshl_add_u64 v[72:73], v[72:73], 0, v[114:115]
	v_add_u32_e32 v88, 0x80, v209
	v_cvt_pk_bf16_f32 v70, v74, v75
	global_store_dwordx4 v[72:73], v[64:67], off
	global_store_dwordx4 v[72:73], v[68:71], off offset:64
	s_nop 0
	v_lshlrev_b32_e32 v64, 7, v88
	v_and_b32_e32 v154, 0x3ff80, v64
	v_lshl_add_u64 v[64:65], s[6:7], 0, v[154:155]
	v_lshl_add_u64 v[72:73], s[8:9], 0, v[154:155]
	v_lshl_add_u64 v[68:69], v[64:65], 0, v[130:131]
	v_lshl_add_u64 v[76:77], v[72:73], 0, v[130:131]
	s_waitcnt vmcnt(2)
; __device__ __forceinline__ unsigned pk2(float lo, float hi) { unsigned r; asm("v_cvt_pk_bf16_f32 %0, %1, %2" : "=v"(r) : "v"(lo), "v"(hi)); return r; }
;     __device__ __forceinline__ void operator()(const f32x4 (&acc)[2][2][4][2], const Unit& uu, int wr, int wc, int fr, int fq) const {
;     ...
;             for (int ai = 0; ai < 2; ++ai)
; #pragma unroll
;                 for (int m = 0; m < 4; ++m) {
;                     const int r = rowb + 128 * ai + 16 * m, s = r & 2047;
;                     u32x4 w1, w2;
;                     {
;                         const f32x4 c0 = *(const f32x4*)(rac + s * 32 + 8 * fq), s0 = *(const f32x4*)(ras + s * 32 + 8 * fq);
;                         const f32x4 c1 = *(const f32x4*)(rac + s * 32 + 8 * fq + 4), s1 = *(const f32x4*)(ras + s * 32 + 8 * fq + 4);
;                         const f32x4 x10 = acc[ai][0][m][0], x11 = acc[ai][0][m][1], x20 = acc[ai][1][m][0], x21 = acc[ai][1][m][1];
;                         const f32x4 a0 = (x10 * c0 - x20 * s0) * qs, a1 = (x11 * c1 - x21 * s1) * qs;
;                         const f32x4 b0 = (x20 * c0 + x10 * s0) * qs, b1 = (x21 * c1 + x11 * s1) * qs;
;                         w1.x = pk2(a0[0], a0[1]); w1.y = pk2(a0[2], a0[3]); w1.z = pk2(a1[0], a1[1]); w1.w = pk2(a1[2], a1[3]);
;                         w2.x = pk2(b0[0], b0[1]); w2.y = pk2(b0[2], b0[3]); w2.z = pk2(b1[0], b1[1]); w2.w = pk2(b1[2], b1[3]);
;                     }
;                     bf16_t* dst = P + (size_t)r * PW + 64 * ch + 8 * fq;
;                     *(u32x4*)dst = w1; *(u32x4*)(dst + 32) = w2;
;                 }
	v_mov_b32_e32 v64, v158
	v_mov_b32_e32 v65, v159
	v_mov_b32_e32 v66, v160
	v_mov_b32_e32 v67, v161
	v_mov_b32_e32 v68, v162
	v_mov_b32_e32 v69, v163
	v_mov_b32_e32 v70, v164
	v_mov_b32_e32 v71, v165
	v_mov_b32_e32 v72, v166
	v_mov_b32_e32 v73, v167
	v_mov_b32_e32 v74, v168
	v_mov_b32_e32 v75, v169
	v_mov_b32_e32 v76, v170
	v_mov_b32_e32 v77, v171
	v_mov_b32_e32 v78, v172
	v_mov_b32_e32 v79, v173
	v_add_u32_e32 v175, 0x90, v209
	v_lshlrev_b32_e32 v175, 7, v175
	v_and_b32_e32 v175, 0x3ff80, v175
	v_add_u32_e32 v175, v130, v175
	global_load_dwordx4 v[158:161], v175, s[6:7] offset:16
	global_load_dwordx4 v[162:165], v175, s[6:7]
	global_load_dwordx4 v[166:169], v175, s[8:9] offset:16
	global_load_dwordx4 v[170:173], v175, s[8:9]
	v_pk_mul_f32 v[84:85], v[50:51], v[74:75]
	v_pk_mul_f32 v[80:81], v[54:55], v[78:79]
	v_pk_mul_f32 v[82:83], v[52:53], v[76:77]
	v_pk_fma_f32 v[80:81], v[62:63], v[70:71], v[80:81] neg_lo:[0,0,1] neg_hi:[0,0,1]
	v_pk_fma_f32 v[82:83], v[60:61], v[68:69], v[82:83] neg_lo:[0,0,1] neg_hi:[0,0,1]
	v_pk_mul_f32 v[86:87], v[48:49], v[72:73]
	v_pk_fma_f32 v[84:85], v[58:59], v[66:67], v[84:85] neg_lo:[0,0,1] neg_hi:[0,0,1]
	v_pk_mul_f32 v[62:63], v[62:63], v[78:79]
	v_pk_mul_f32 v[60:61], v[60:61], v[76:77]
	v_pk_mul_f32 v[58:59], v[58:59], v[74:75]
	v_pk_fma_f32 v[86:87], v[56:57], v[64:65], v[86:87] neg_lo:[0,0,1] neg_hi:[0,0,1]
	v_pk_fma_f32 v[54:55], v[54:55], v[70:71], v[62:63]
	v_pk_fma_f32 v[52:53], v[52:53], v[68:69], v[60:61]
	v_pk_mul_f32 v[56:57], v[56:57], v[72:73]
	v_pk_fma_f32 v[50:51], v[50:51], v[66:67], v[58:59]
	v_pk_mul_f32 v[54:55], v[128:129], v[54:55] op_sel_hi:[0,1]
	v_pk_mul_f32 v[52:53], v[128:129], v[52:53] op_sel_hi:[0,1]
	v_pk_fma_f32 v[48:49], v[48:49], v[64:65], v[56:57]
	v_pk_mul_f32 v[56:57], v[128:129], v[50:51] op_sel_hi:[0,1]
	v_cvt_pk_bf16_f32 v52, v52, v53
	v_cvt_pk_bf16_f32 v53, v54, v55
	v_cvt_pk_bf16_f32 v55, v56, v57
	v_mad_i64_i32 v[56:57], s[24:25], v88, s17, v[112:113]
	v_lshl_add_u64 v[56:57], v[56:57], 0, s[2:3]
	v_pk_mul_f32 v[80:81], v[128:129], v[80:81] op_sel_hi:[0,1]
	v_pk_mul_f32 v[82:83], v[128:129], v[82:83] op_sel_hi:[0,1]
	v_pk_mul_f32 v[84:85], v[128:129], v[84:85] op_sel_hi:[0,1]
	v_pk_mul_f32 v[86:87], v[128:129], v[86:87] op_sel_hi:[0,1]
	v_pk_mul_f32 v[58:59], v[128:129], v[48:49] op_sel_hi:[0,1]
	v_cvt_pk_bf16_f32 v48, v82, v83
	v_cvt_pk_bf16_f32 v49, v80, v81
	v_cvt_pk_bf16_f32 v50, v86, v87
	v_cvt_pk_bf16_f32 v51, v84, v85
	v_lshl_add_u64 v[56:57], v[56:57], 0, v[114:115]
	v_add_u32_e32 v72, 0x90, v209
	v_cvt_pk_bf16_f32 v54, v58, v59
	global_store_dwordx4 v[56:57], v[48:51], off
	global_store_dwordx4 v[56:57], v[52:55], off offset:64
	s_nop 0
	v_lshlrev_b32_e32 v48, 7, v72
	v_and_b32_e32 v154, 0x3ff80, v48
	v_lshl_add_u64 v[48:49], s[6:7], 0, v[154:155]
	v_lshl_add_u64 v[56:57], s[8:9], 0, v[154:155]
	v_lshl_add_u64 v[52:53], v[48:49], 0, v[130:131]
	v_lshl_add_u64 v[60:61], v[56:57], 0, v[130:131]
	s_waitcnt vmcnt(2)
	v_mov_b32_e32 v48, v158
	v_mov_b32_e32 v49, v159
	v_mov_b32_e32 v50, v160
	v_mov_b32_e32 v51, v161
	v_mov_b32_e32 v52, v162
	v_mov_b32_e32 v53, v163
	v_mov_b32_e32 v54, v164
	v_mov_b32_e32 v55, v165
	v_mov_b32_e32 v56, v166
	v_mov_b32_e32 v57, v167
	v_mov_b32_e32 v58, v168
	v_mov_b32_e32 v59, v169
	v_mov_b32_e32 v60, v170
	v_mov_b32_e32 v61, v171
	v_mov_b32_e32 v62, v172
	v_mov_b32_e32 v63, v173
	v_add_u32_e32 v175, 0xa0, v209
	v_lshlrev_b32_e32 v175, 7, v175
	v_and_b32_e32 v175, 0x3ff80, v175
	v_add_u32_e32 v175, v130, v175
	global_load_dwordx4 v[158:161], v175, s[6:7] offset:16
	global_load_dwordx4 v[162:165], v175, s[6:7]
	global_load_dwordx4 v[166:169], v175, s[8:9] offset:16
	global_load_dwordx4 v[170:173], v175, s[8:9]
	v_pk_mul_f32 v[68:69], v[34:35], v[58:59]
	v_pk_mul_f32 v[64:65], v[38:39], v[62:63]
	v_pk_mul_f32 v[66:67], v[36:37], v[60:61]
	v_pk_fma_f32 v[64:65], v[46:47], v[54:55], v[64:65] neg_lo:[0,0,1] neg_hi:[0,0,1]
	v_pk_fma_f32 v[66:67], v[44:45], v[52:53], v[66:67] neg_lo:[0,0,1] neg_hi:[0,0,1]
	v_pk_mul_f32 v[70:71], v[32:33], v[56:57]
	v_pk_fma_f32 v[68:69], v[42:43], v[50:51], v[68:69] neg_lo:[0,0,1] neg_hi:[0,0,1]
	v_pk_mul_f32 v[46:47], v[46:47], v[62:63]
	v_pk_mul_f32 v[44:45], v[44:45], v[60:61]
	v_pk_mul_f32 v[42:43], v[42:43], v[58:59]
	v_pk_fma_f32 v[70:71], v[40:41], v[48:49], v[70:71] neg_lo:[0,0,1] neg_hi:[0,0,1]
	v_pk_fma_f32 v[38:39], v[38:39], v[54:55], v[46:47]
	v_pk_fma_f32 v[36:37], v[36:37], v[52:53], v[44:45]
	v_pk_mul_f32 v[40:41], v[40:41], v[56:57]
	v_pk_fma_f32 v[34:35], v[34:35], v[50:51], v[42:43]
	v_pk_mul_f32 v[38:39], v[128:129], v[38:39] op_sel_hi:[0,1]
	v_pk_mul_f32 v[36:37], v[128:129], v[36:37] op_sel_hi:[0,1]
	v_pk_fma_f32 v[32:33], v[32:33], v[48:49], v[40:41]
	v_pk_mul_f32 v[40:41], v[128:129], v[34:35] op_sel_hi:[0,1]
	v_cvt_pk_bf16_f32 v36, v36, v37
	v_cvt_pk_bf16_f32 v37, v38, v39
	v_cvt_pk_bf16_f32 v39, v40, v41
	v_mad_i64_i32 v[40:41], s[24:25], v72, s17, v[112:113]
	v_lshl_add_u64 v[40:41], v[40:41], 0, s[2:3]
	v_pk_mul_f32 v[64:65], v[128:129], v[64:65] op_sel_hi:[0,1]
	v_pk_mul_f32 v[66:67], v[128:129], v[66:67] op_sel_hi:[0,1]
	v_pk_mul_f32 v[68:69], v[128:129], v[68:69] op_sel_hi:[0,1]
	v_pk_mul_f32 v[70:71], v[128:129], v[70:71] op_sel_hi:[0,1]
	v_pk_mul_f32 v[42:43], v[128:129], v[32:33] op_sel_hi:[0,1]
	v_cvt_pk_bf16_f32 v32, v66, v67
	v_cvt_pk_bf16_f32 v33, v64, v65
	v_cvt_pk_bf16_f32 v34, v70, v71
	v_cvt_pk_bf16_f32 v35, v68, v69
	v_lshl_add_u64 v[40:41], v[40:41], 0, v[114:115]
	v_add_u32_e32 v56, 0xa0, v209
	v_cvt_pk_bf16_f32 v38, v42, v43
	global_store_dwordx4 v[40:41], v[32:35], off
	global_store_dwordx4 v[40:41], v[36:39], off offset:64
	s_nop 0
	v_lshlrev_b32_e32 v32, 7, v56
	v_and_b32_e32 v154, 0x3ff80, v32
	v_lshl_add_u64 v[32:33], s[6:7], 0, v[154:155]
	v_lshl_add_u64 v[40:41], s[8:9], 0, v[154:155]
	v_lshl_add_u64 v[36:37], v[32:33], 0, v[130:131]
	v_lshl_add_u64 v[44:45], v[40:41], 0, v[130:131]
	s_waitcnt vmcnt(2)
; __device__ __forceinline__ unsigned pk2(float lo, float hi) { unsigned r; asm("v_cvt_pk_bf16_f32 %0, %1, %2" : "=v"(r) : "v"(lo), "v"(hi)); return r; }
;     __device__ __forceinline__ void operator()(const f32x4 (&acc)[2][2][4][2], const Unit& uu, int wr, int wc, int fr, int fq) const {
;     ...
;             for (int ai = 0; ai < 2; ++ai)
; #pragma unroll
;                 for (int m = 0; m < 4; ++m) {
;                     const int r = rowb + 128 * ai + 16 * m, s = r & 2047;
;                     u32x4 w1, w2;
;                     {
;                         const f32x4 c0 = *(const f32x4*)(rac + s * 32 + 8 * fq), s0 = *(const f32x4*)(ras + s * 32 + 8 * fq);
;                         const f32x4 c1 = *(const f32x4*)(rac + s * 32 + 8 * fq + 4), s1 = *(const f32x4*)(ras + s * 32 + 8 * fq + 4);
;                         const f32x4 x10 = acc[ai][0][m][0], x11 = acc[ai][0][m][1], x20 = acc[ai][1][m][0], x21 = acc[ai][1][m][1];
;                         const f32x4 a0 = (x10 * c0 - x20 * s0) * qs, a1 = (x11 * c1 - x21 * s1) * qs;
;                         const f32x4 b0 = (x20 * c0 + x10 * s0) * qs, b1 = (x21 * c1 + x11 * s1) * qs;
;                         w1.x = pk2(a0[0], a0[1]); w1.y = pk2(a0[2], a0[3]); w1.z = pk2(a1[0], a1[1]); w1.w = pk2(a1[2], a1[3]);
;                         w2.x = pk2(b0[0], b0[1]); w2.y = pk2(b0[2], b0[3]); w2.z = pk2(b1[0], b1[1]); w2.w = pk2(b1[2], b1[3]);
;                     }
;                     bf16_t* dst = P + (size_t)r * PW + 64 * ch + 8 * fq;
;                     *(u32x4*)dst = w1; *(u32x4*)(dst + 32) = w2;
;                 }
	v_mov_b32_e32 v32, v158
	v_mov_b32_e32 v33, v159
	v_mov_b32_e32 v34, v160
	v_mov_b32_e32 v35, v161
	v_mov_b32_e32 v36, v162
	v_mov_b32_e32 v37, v163
	v_mov_b32_e32 v38, v164
	v_mov_b32_e32 v39, v165
	v_mov_b32_e32 v40, v166
	v_mov_b32_e32 v41, v167
	v_mov_b32_e32 v42, v168
	v_mov_b32_e32 v43, v169
	v_mov_b32_e32 v44, v170
	v_mov_b32_e32 v45, v171
	v_mov_b32_e32 v46, v172
	v_mov_b32_e32 v47, v173
	v_add_u32_e32 v175, 0xb0, v209
	v_lshlrev_b32_e32 v175, 7, v175
	v_and_b32_e32 v175, 0x3ff80, v175
	v_add_u32_e32 v175, v130, v175
	global_load_dwordx4 v[158:161], v175, s[6:7] offset:16
	global_load_dwordx4 v[162:165], v175, s[6:7]
	global_load_dwordx4 v[166:169], v175, s[8:9] offset:16
	global_load_dwordx4 v[170:173], v175, s[8:9]
	v_pk_mul_f32 v[52:53], v[18:19], v[42:43]
	v_pk_mul_f32 v[48:49], v[22:23], v[46:47]
	v_pk_mul_f32 v[50:51], v[20:21], v[44:45]
	v_pk_fma_f32 v[48:49], v[30:31], v[38:39], v[48:49] neg_lo:[0,0,1] neg_hi:[0,0,1]
	v_pk_fma_f32 v[50:51], v[28:29], v[36:37], v[50:51] neg_lo:[0,0,1] neg_hi:[0,0,1]
	v_pk_mul_f32 v[54:55], v[16:17], v[40:41]
	v_pk_fma_f32 v[52:53], v[26:27], v[34:35], v[52:53] neg_lo:[0,0,1] neg_hi:[0,0,1]
	v_pk_mul_f32 v[30:31], v[30:31], v[46:47]
	v_pk_mul_f32 v[28:29], v[28:29], v[44:45]
	v_pk_mul_f32 v[26:27], v[26:27], v[42:43]
	v_pk_fma_f32 v[54:55], v[24:25], v[32:33], v[54:55] neg_lo:[0,0,1] neg_hi:[0,0,1]
	v_pk_fma_f32 v[22:23], v[22:23], v[38:39], v[30:31]
	v_pk_fma_f32 v[20:21], v[20:21], v[36:37], v[28:29]
	v_pk_mul_f32 v[24:25], v[24:25], v[40:41]
	v_pk_fma_f32 v[18:19], v[18:19], v[34:35], v[26:27]
	v_pk_mul_f32 v[22:23], v[128:129], v[22:23] op_sel_hi:[0,1]
	v_pk_mul_f32 v[20:21], v[128:129], v[20:21] op_sel_hi:[0,1]
	v_pk_fma_f32 v[16:17], v[16:17], v[32:33], v[24:25]
	v_pk_mul_f32 v[24:25], v[128:129], v[18:19] op_sel_hi:[0,1]
	v_cvt_pk_bf16_f32 v20, v20, v21
	v_cvt_pk_bf16_f32 v21, v22, v23
	v_cvt_pk_bf16_f32 v23, v24, v25
	v_mad_i64_i32 v[24:25], s[24:25], v56, s17, v[112:113]
	v_lshl_add_u64 v[24:25], v[24:25], 0, s[2:3]
	v_pk_mul_f32 v[48:49], v[128:129], v[48:49] op_sel_hi:[0,1]
	v_pk_mul_f32 v[50:51], v[128:129], v[50:51] op_sel_hi:[0,1]
	v_pk_mul_f32 v[52:53], v[128:129], v[52:53] op_sel_hi:[0,1]
	v_pk_mul_f32 v[54:55], v[128:129], v[54:55] op_sel_hi:[0,1]
	v_pk_mul_f32 v[26:27], v[128:129], v[16:17] op_sel_hi:[0,1]
	v_cvt_pk_bf16_f32 v16, v50, v51
	v_cvt_pk_bf16_f32 v17, v48, v49
	v_cvt_pk_bf16_f32 v18, v54, v55
	v_cvt_pk_bf16_f32 v19, v52, v53
	v_lshl_add_u64 v[24:25], v[24:25], 0, v[114:115]
	v_add_u32_e32 v40, 0xb0, v209
	v_cvt_pk_bf16_f32 v22, v26, v27
	global_store_dwordx4 v[24:25], v[16:19], off
	global_store_dwordx4 v[24:25], v[20:23], off offset:64
	s_nop 0
	v_lshlrev_b32_e32 v16, 7, v40
	v_and_b32_e32 v154, 0x3ff80, v16
	v_lshl_add_u64 v[16:17], s[6:7], 0, v[154:155]
	v_lshl_add_u64 v[24:25], s[8:9], 0, v[154:155]
	v_lshl_add_u64 v[20:21], v[16:17], 0, v[130:131]
	v_lshl_add_u64 v[28:29], v[24:25], 0, v[130:131]
	s_waitcnt vmcnt(2)
	v_mov_b32_e32 v16, v158
	v_mov_b32_e32 v17, v159
	v_mov_b32_e32 v18, v160
	v_mov_b32_e32 v19, v161
	v_mov_b32_e32 v20, v162
	v_mov_b32_e32 v21, v163
	v_mov_b32_e32 v22, v164
	v_mov_b32_e32 v23, v165
	v_mov_b32_e32 v24, v166
	v_mov_b32_e32 v25, v167
	v_mov_b32_e32 v26, v168
	v_mov_b32_e32 v27, v169
	v_mov_b32_e32 v28, v170
	v_mov_b32_e32 v29, v171
	v_mov_b32_e32 v30, v172
	v_mov_b32_e32 v31, v173
	v_pk_mul_f32 v[36:37], v[2:3], v[26:27]
	v_pk_mul_f32 v[32:33], v[6:7], v[30:31]
	v_pk_mul_f32 v[34:35], v[4:5], v[28:29]
	v_pk_fma_f32 v[32:33], v[14:15], v[22:23], v[32:33] neg_lo:[0,0,1] neg_hi:[0,0,1]
	v_pk_fma_f32 v[34:35], v[12:13], v[20:21], v[34:35] neg_lo:[0,0,1] neg_hi:[0,0,1]
	v_pk_mul_f32 v[38:39], v[0:1], v[24:25]
	v_pk_fma_f32 v[36:37], v[10:11], v[18:19], v[36:37] neg_lo:[0,0,1] neg_hi:[0,0,1]
	v_pk_mul_f32 v[14:15], v[14:15], v[30:31]
	v_pk_mul_f32 v[12:13], v[12:13], v[28:29]
	v_pk_mul_f32 v[10:11], v[10:11], v[26:27]
	v_pk_fma_f32 v[38:39], v[8:9], v[16:17], v[38:39] neg_lo:[0,0,1] neg_hi:[0,0,1]
	v_pk_fma_f32 v[6:7], v[6:7], v[22:23], v[14:15]
	v_pk_fma_f32 v[4:5], v[4:5], v[20:21], v[12:13]
	v_pk_mul_f32 v[8:9], v[8:9], v[24:25]
	v_pk_fma_f32 v[2:3], v[2:3], v[18:19], v[10:11]
	v_pk_mul_f32 v[6:7], v[128:129], v[6:7] op_sel_hi:[0,1]
	v_pk_mul_f32 v[4:5], v[128:129], v[4:5] op_sel_hi:[0,1]
	v_pk_fma_f32 v[0:1], v[0:1], v[16:17], v[8:9]
	v_pk_mul_f32 v[8:9], v[128:129], v[2:3] op_sel_hi:[0,1]
	v_cvt_pk_bf16_f32 v4, v4, v5
	v_cvt_pk_bf16_f32 v5, v6, v7
	v_cvt_pk_bf16_f32 v7, v8, v9
	v_mad_i64_i32 v[8:9], s[24:25], v40, s17, v[112:113]
	v_lshl_add_u64 v[8:9], v[8:9], 0, s[2:3]
	v_pk_mul_f32 v[32:33], v[128:129], v[32:33] op_sel_hi:[0,1]
	v_pk_mul_f32 v[34:35], v[128:129], v[34:35] op_sel_hi:[0,1]
	v_pk_mul_f32 v[36:37], v[128:129], v[36:37] op_sel_hi:[0,1]
	v_pk_mul_f32 v[38:39], v[128:129], v[38:39] op_sel_hi:[0,1]
	v_pk_mul_f32 v[10:11], v[128:129], v[0:1] op_sel_hi:[0,1]
	v_cvt_pk_bf16_f32 v0, v34, v35
	v_cvt_pk_bf16_f32 v1, v32, v33
	v_cvt_pk_bf16_f32 v2, v38, v39
	v_cvt_pk_bf16_f32 v3, v36, v37
	v_lshl_add_u64 v[8:9], v[8:9], 0, v[114:115]
	v_cvt_pk_bf16_f32 v6, v10, v11
	global_store_dwordx4 v[8:9], v[0:3], off
	global_store_dwordx4 v[8:9], v[4:7], off offset:64
	s_branch .LBB0_315
